# nt hint on the phase-7 x1 loads and the phase-4 gate loads (read once each)
# speedup vs baseline: 1.0142x; 1.0021x over previous
; #define PG8_STAGE(bufoff, gbase, voff) do { _Pragma("unroll") for (int _i = 0; _i < 2; ++_i) \
;         __builtin_amdgcn_global_load_lds((const unsigned*)((const char*)(gbase) + (voff)[_i]), (PG8_LAS unsigned*)(lds + (bufoff) + ldsw + _i * 8192), 16, 0, 0); } while (0)
; #define PG8_LDA(dst, b, h) do { _Pragma("unroll") for (int m = 0; m < 4; ++m) _Pragma("unroll") for (int k = 0; k < 2; ++k) dst[m][k] = *(const PG8_LAS bf16x8*)(lds + PG8_SA(b, h) + aoff + m * 2048 + k * 1024); } while (0)
; #define PG8_LDB(dst, b, h) do { _Pragma("unroll") for (int n = 0; n < 2; ++n) _Pragma("unroll") for (int k = 0; k < 2; ++k) dst[n][k] = *(const PG8_LAS bf16x8*)(lds + PG8_SB(b, h) + boff + n * 2048 + k * 1024); } while (0)
; #define PG8_MMA(ai, bj, At, Bt) do { __builtin_amdgcn_s_setprio(1); _Pragma("unroll") for (int m = 0; m < 4; ++m) _Pragma("unroll") for (int n = 0; n < 2; ++n) _Pragma("unroll") for (int k = 0; k < 2; ++k) \
;         acc[ai][bj][m][n] = __builtin_amdgcn_mfma_f32_16x16x32_bf16(Bt[n][k], At[m][k], acc[ai][bj][m][n], 0, 0, 0); __builtin_amdgcn_s_setprio(0); } while (0)
; #define PG8_WAIT_L(n) asm volatile("s_waitcnt lgkmcnt(" #n ")" ::: "memory")
; #define PG8_BAR __builtin_amdgcn_s_barrier()
; #define PG8_SCHED __builtin_amdgcn_sched_barrier(0)
; template <class Epi, class Sched>
; __device__ __forceinline__ void gemm_phase(PG8_LAS unsigned char* lds, const Gemm g, const Sched& S, const Epi& E) {
;     ...
;             PG8_LDB(B0, 0, 0); PG8_SCHED; PG8_LDA(At, 0, 0); PG8_STAGE(PG8_SA(1, 1), a1 + hstep, voffA);
;             PG8_WAIT_L(8); PG8_BAR; PG8_WAIT_L(0); PG8_MMA(0, 0, At, B0); PG8_BAR; PG8_SCHED;
;             PG8_LDB(B1, 0, 1); PG8_STAGE(PG8_SB(0, 0), b2, voffB);
;             PG8_BAR; PG8_WAIT_L(0); PG8_MMA(0, 1, At, B1); PG8_BAR;
;             PG8_LDA(At, 0, 1); PG8_STAGE(PG8_SA(0, 0), a2, voffA);
;             PG8_BAR; PG8_WAIT_L(0); PG8_MMA(1, 0, At, B0); PG8_BAR; PG8_SCHED;
.LBB0_694:
	ds_read_b128 v[138:141], v157
	ds_read_b128 v[142:145], v158
	ds_read_b128 v[174:177], v159
	ds_read_b128 v[178:181], v160
	s_add_u32 s30, s28, 0xfffe0080
	s_addc_u32 s31, s29, -1
	s_cmp_eq_u32 s63, 4
	s_cselect_b32 s35, s17, s31
	s_cselect_b32 s34, s59, s30
	s_cselect_b32 s31, s15, s62
	s_cselect_b32 s30, s60, s61
	s_mov_b32 m0, s57
	v_lshl_add_u64 v[214:215], s[28:29], 0, v[134:135]
	ds_read_b128 v[182:185], v155
	ds_read_b128 v[186:189], v155 offset:1024
	ds_read_b128 v[190:193], v155 offset:2048
	ds_read_b128 v[194:197], v155 offset:3072
	ds_read_b128 v[198:201], v155 offset:4096
	ds_read_b128 v[202:205], v155 offset:5120
	ds_read_b128 v[206:209], v155 offset:6144
	ds_read_b128 v[210:213], v155 offset:7168
	global_load_lds_dwordx4 v[214:215], off
	v_lshl_add_u64 v[214:215], s[28:29], 0, v[136:137]
	s_mov_b32 m0, s58
	s_nop 0
	global_load_lds_dwordx4 v[214:215], off
	s_waitcnt lgkmcnt(8)
	s_barrier
	s_waitcnt lgkmcnt(0)
	s_setprio 1
	s_waitcnt lgkmcnt(0)
	v_mfma_f32_16x16x32_bf16 v[126:129], v[138:141], v[182:185], v[126:129]
	v_mfma_f32_16x16x32_bf16 v[122:125], v[174:177], v[182:185], v[122:125]
	v_mfma_f32_16x16x32_bf16 v[118:121], v[138:141], v[190:193], v[118:121]
	v_mfma_f32_16x16x32_bf16 v[106:109], v[174:177], v[190:193], v[106:109]
	v_mfma_f32_16x16x32_bf16 v[98:101], v[138:141], v[198:201], v[98:101]
	v_mfma_f32_16x16x32_bf16 v[94:97], v[174:177], v[198:201], v[94:97]
	v_mfma_f32_16x16x32_bf16 v[86:89], v[138:141], v[206:209], v[86:89]
	v_mfma_f32_16x16x32_bf16 v[78:81], v[174:177], v[206:209], v[78:81]
	v_mfma_f32_16x16x32_bf16 v[126:129], v[142:145], v[186:189], v[126:129]
	v_mfma_f32_16x16x32_bf16 v[122:125], v[178:181], v[186:189], v[122:125]
	v_mfma_f32_16x16x32_bf16 v[118:121], v[142:145], v[194:197], v[118:121]
	v_mfma_f32_16x16x32_bf16 v[106:109], v[178:181], v[194:197], v[106:109]
	v_mfma_f32_16x16x32_bf16 v[98:101], v[142:145], v[202:205], v[98:101]
	v_mfma_f32_16x16x32_bf16 v[94:97], v[178:181], v[202:205], v[94:97]
	v_mfma_f32_16x16x32_bf16 v[86:89], v[142:145], v[210:213], v[86:89]
	v_mfma_f32_16x16x32_bf16 v[78:81], v[178:181], v[210:213], v[78:81]
	s_setprio 0
	s_barrier
	s_mov_b32 m0, s25
	v_lshl_add_u64 v[230:231], s[30:31], 0, v[130:131]
	ds_read_b128 v[214:217], v161
	ds_read_b128 v[218:221], v162
	ds_read_b128 v[222:225], v163
	ds_read_b128 v[226:229], v164
	global_load_lds_dwordx4 v[230:231], off
	v_lshl_add_u64 v[232:233], s[30:31], 0, v[132:133]
	s_mov_b32 m0, s27
	s_nop 0
	global_load_lds_dwordx4 v[232:233], off
	s_barrier
	s_waitcnt lgkmcnt(0)
	s_setprio 1
	s_waitcnt lgkmcnt(0)
	v_mfma_f32_16x16x32_bf16 v[114:117], v[214:217], v[182:185], v[114:117]
	v_mfma_f32_16x16x32_bf16 v[110:113], v[222:225], v[182:185], v[110:113]
	v_mfma_f32_16x16x32_bf16 v[102:105], v[214:217], v[190:193], v[102:105]
	v_mfma_f32_16x16x32_bf16 v[90:93], v[222:225], v[190:193], v[90:93]
	v_mfma_f32_16x16x32_bf16 v[82:85], v[214:217], v[198:201], v[82:85]
	v_mfma_f32_16x16x32_bf16 v[70:73], v[222:225], v[198:201], v[70:73]
	v_mfma_f32_16x16x32_bf16 v[74:77], v[214:217], v[206:209], v[74:77]
	v_mfma_f32_16x16x32_bf16 v[66:69], v[222:225], v[206:209], v[66:69]
	v_mfma_f32_16x16x32_bf16 v[114:117], v[218:221], v[186:189], v[114:117]
	v_mfma_f32_16x16x32_bf16 v[110:113], v[226:229], v[186:189], v[110:113]
	v_mfma_f32_16x16x32_bf16 v[102:105], v[218:221], v[194:197], v[102:105]
	v_mfma_f32_16x16x32_bf16 v[90:93], v[226:229], v[194:197], v[90:93]
	v_mfma_f32_16x16x32_bf16 v[82:85], v[218:221], v[202:205], v[82:85]
	v_mfma_f32_16x16x32_bf16 v[70:73], v[226:229], v[202:205], v[70:73]
	v_mfma_f32_16x16x32_bf16 v[74:77], v[218:221], v[210:213], v[74:77]
	v_mfma_f32_16x16x32_bf16 v[66:69], v[226:229], v[210:213], v[66:69]
	s_setprio 0
	s_mov_b32 m0, s40
	v_lshl_add_u64 v[234:235], s[34:35], 0, v[130:131]
	s_barrier
	ds_read_b128 v[182:185], v155 offset:16384
	ds_read_b128 v[186:189], v155 offset:17408
	ds_read_b128 v[190:193], v155 offset:18432
	ds_read_b128 v[194:197], v155 offset:19456
	ds_read_b128 v[198:201], v155 offset:20480
	ds_read_b128 v[202:205], v155 offset:21504
	ds_read_b128 v[206:209], v155 offset:22528
	ds_read_b128 v[210:213], v155 offset:23552
	global_load_lds_dwordx4 v[234:235], off
	v_lshl_add_u64 v[236:237], s[34:35], 0, v[132:133]
	s_mov_b32 m0, s41
	s_nop 0
	global_load_lds_dwordx4 v[236:237], off
	s_barrier
	s_waitcnt lgkmcnt(0)
	s_setprio 1
	s_waitcnt lgkmcnt(0)
	v_mfma_f32_16x16x32_bf16 v[62:65], v[138:141], v[182:185], v[62:65]
	v_mfma_f32_16x16x32_bf16 v[58:61], v[174:177], v[182:185], v[58:61]
	v_mfma_f32_16x16x32_bf16 v[50:53], v[138:141], v[190:193], v[50:53]
	v_mfma_f32_16x16x32_bf16 v[42:45], v[174:177], v[190:193], v[42:45]
	v_mfma_f32_16x16x32_bf16 v[30:33], v[138:141], v[198:201], v[30:33]
	v_mfma_f32_16x16x32_bf16 v[26:29], v[174:177], v[198:201], v[26:29]
	v_mfma_f32_16x16x32_bf16 v[14:17], v[138:141], v[206:209], v[14:17]
	v_mfma_f32_16x16x32_bf16 v[10:13], v[174:177], v[206:209], v[10:13]
	v_mfma_f32_16x16x32_bf16 v[62:65], v[142:145], v[186:189], v[62:65]
	v_mfma_f32_16x16x32_bf16 v[58:61], v[178:181], v[186:189], v[58:61]
	v_mfma_f32_16x16x32_bf16 v[50:53], v[142:145], v[194:197], v[50:53]
	v_mfma_f32_16x16x32_bf16 v[42:45], v[178:181], v[194:197], v[42:45]
	v_mfma_f32_16x16x32_bf16 v[30:33], v[142:145], v[202:205], v[30:33]
	v_mfma_f32_16x16x32_bf16 v[26:29], v[178:181], v[202:205], v[26:29]
	v_mfma_f32_16x16x32_bf16 v[14:17], v[142:145], v[210:213], v[14:17]
	v_mfma_f32_16x16x32_bf16 v[10:13], v[178:181], v[210:213], v[10:13]
	s_setprio 0
	s_barrier
; #define PG8_STAGE(bufoff, gbase, voff) do { _Pragma("unroll") for (int _i = 0; _i < 2; ++_i) \
;         __builtin_amdgcn_global_load_lds((const unsigned*)((const char*)(gbase) + (voff)[_i]), (PG8_LAS unsigned*)(lds + (bufoff) + ldsw + _i * 8192), 16, 0, 0); } while (0)
; #define PG8_LDA(dst, b, h) do { _Pragma("unroll") for (int m = 0; m < 4; ++m) _Pragma("unroll") for (int k = 0; k < 2; ++k) dst[m][k] = *(const PG8_LAS bf16x8*)(lds + PG8_SA(b, h) + aoff + m * 2048 + k * 1024); } while (0)
; #define PG8_LDB(dst, b, h) do { _Pragma("unroll") for (int n = 0; n < 2; ++n) _Pragma("unroll") for (int k = 0; k < 2; ++k) dst[n][k] = *(const PG8_LAS bf16x8*)(lds + PG8_SB(b, h) + boff + n * 2048 + k * 1024); } while (0)
; #define PG8_MMA(ai, bj, At, Bt) do { __builtin_amdgcn_s_setprio(1); _Pragma("unroll") for (int m = 0; m < 4; ++m) _Pragma("unroll") for (int n = 0; n < 2; ++n) _Pragma("unroll") for (int k = 0; k < 2; ++k) \
;         acc[ai][bj][m][n] = __builtin_amdgcn_mfma_f32_16x16x32_bf16(Bt[n][k], At[m][k], acc[ai][bj][m][n], 0, 0, 0); __builtin_amdgcn_s_setprio(0); } while (0)
; #define PG8_WAIT_V(n) asm volatile("s_waitcnt vmcnt(" #n ")" ::: "memory")
; #define PG8_WAIT_L(n) asm volatile("s_waitcnt lgkmcnt(" #n ")" ::: "memory")
; #define PG8_BAR __builtin_amdgcn_s_barrier()
; #define PG8_SCHED __builtin_amdgcn_sched_barrier(0)
; template <class Epi, class Sched>
; __device__ __forceinline__ void gemm_phase(PG8_LAS unsigned char* lds, const Gemm g, const Sched& S, const Epi& E) {
;     ...
;             PG8_STAGE(PG8_SB(0, 1), b2 + hstep, voffB);
;             PG8_WAIT_V(6); PG8_BAR; PG8_MMA(1, 1, At, B1); PG8_BAR;
;             PG8_LDB(B0, 1, 0); PG8_SCHED; PG8_LDA(At, 1, 0); PG8_STAGE(PG8_SA(0, 1), a2 + hstep, voffA);
;             PG8_WAIT_L(8); PG8_BAR; PG8_WAIT_L(0); PG8_MMA(0, 0, At, B0); PG8_BAR; PG8_SCHED;
;             PG8_LDB(B1, 1, 1); PG8_STAGE(PG8_SB(1, 0), b3, voffB);
;             PG8_BAR; PG8_WAIT_L(0); PG8_MMA(0, 1, At, B1); PG8_BAR;
;             PG8_LDA(At, 1, 1); PG8_STAGE(PG8_SA(1, 0), a3, voffA);
;             PG8_BAR; PG8_WAIT_L(0); PG8_MMA(1, 0, At, B0); PG8_BAR; PG8_SCHED;
	s_add_u32 s64, s30, 0x20000
	s_addc_u32 s65, s31, 0
	s_mov_b32 m0, s42
	v_lshl_add_u64 v[138:139], s[64:65], 0, v[130:131]
	global_load_lds_dwordx4 v[138:139], off
	v_lshl_add_u64 v[138:139], s[64:65], 0, v[132:133]
	s_mov_b32 m0, s43
	s_nop 0
	global_load_lds_dwordx4 v[138:139], off
	s_waitcnt vmcnt(6)
	s_barrier
	s_setprio 1
	v_mfma_f32_16x16x32_bf16 v[54:57], v[214:217], v[182:185], v[54:57]
	v_mfma_f32_16x16x32_bf16 v[46:49], v[222:225], v[182:185], v[46:49]
	v_mfma_f32_16x16x32_bf16 v[38:41], v[214:217], v[190:193], v[38:41]
	v_mfma_f32_16x16x32_bf16 v[34:37], v[222:225], v[190:193], v[34:37]
	v_mfma_f32_16x16x32_bf16 v[22:25], v[214:217], v[198:201], v[22:25]
	v_mfma_f32_16x16x32_bf16 v[18:21], v[222:225], v[198:201], v[18:21]
	v_mfma_f32_16x16x32_bf16 v[6:9], v[214:217], v[206:209], v[6:9]
	v_mfma_f32_16x16x32_bf16 v[2:5], v[222:225], v[206:209], v[2:5]
	v_mfma_f32_16x16x32_bf16 v[54:57], v[218:221], v[186:189], v[54:57]
	v_mfma_f32_16x16x32_bf16 v[46:49], v[226:229], v[186:189], v[46:49]
	v_mfma_f32_16x16x32_bf16 v[38:41], v[218:221], v[194:197], v[38:41]
	v_mfma_f32_16x16x32_bf16 v[34:37], v[226:229], v[194:197], v[34:37]
	v_mfma_f32_16x16x32_bf16 v[22:25], v[218:221], v[202:205], v[22:25]
	v_mfma_f32_16x16x32_bf16 v[18:21], v[226:229], v[202:205], v[18:21]
	v_mfma_f32_16x16x32_bf16 v[6:9], v[218:221], v[210:213], v[6:9]
	v_mfma_f32_16x16x32_bf16 v[2:5], v[226:229], v[210:213], v[2:5]
	s_setprio 0
	s_barrier
	ds_read_b128 v[138:141], v165
	ds_read_b128 v[142:145], v166
	ds_read_b128 v[174:177], v167
	ds_read_b128 v[178:181], v168
	s_add_u32 s34, s34, 0x20000
	s_addc_u32 s35, s35, 0
	s_mov_b32 m0, s44
	v_lshl_add_u64 v[214:215], s[34:35], 0, v[130:131]
	ds_read_b128 v[182:185], v155 offset:32768
	ds_read_b128 v[186:189], v155 offset:33792
	ds_read_b128 v[190:193], v155 offset:34816
	ds_read_b128 v[194:197], v155 offset:35840
	ds_read_b128 v[198:201], v155 offset:36864
	ds_read_b128 v[202:205], v155 offset:37888
	ds_read_b128 v[206:209], v155 offset:38912
	ds_read_b128 v[210:213], v155 offset:39936
	global_load_lds_dwordx4 v[214:215], off
	v_lshl_add_u64 v[214:215], s[34:35], 0, v[132:133]
	s_mov_b32 m0, s45
	s_nop 0
	global_load_lds_dwordx4 v[214:215], off
	s_waitcnt lgkmcnt(8)
	s_barrier
	s_waitcnt lgkmcnt(0)
	s_setprio 1
	s_waitcnt lgkmcnt(0)
	v_mfma_f32_16x16x32_bf16 v[126:129], v[138:141], v[182:185], v[126:129]
	v_mfma_f32_16x16x32_bf16 v[122:125], v[174:177], v[182:185], v[122:125]
	v_mfma_f32_16x16x32_bf16 v[118:121], v[138:141], v[190:193], v[118:121]
	v_mfma_f32_16x16x32_bf16 v[106:109], v[174:177], v[190:193], v[106:109]
	v_mfma_f32_16x16x32_bf16 v[98:101], v[138:141], v[198:201], v[98:101]
	v_mfma_f32_16x16x32_bf16 v[94:97], v[174:177], v[198:201], v[94:97]
	v_mfma_f32_16x16x32_bf16 v[86:89], v[138:141], v[206:209], v[86:89]
	v_mfma_f32_16x16x32_bf16 v[78:81], v[174:177], v[206:209], v[78:81]
	v_mfma_f32_16x16x32_bf16 v[126:129], v[142:145], v[186:189], v[126:129]
	v_mfma_f32_16x16x32_bf16 v[122:125], v[178:181], v[186:189], v[122:125]
	v_mfma_f32_16x16x32_bf16 v[118:121], v[142:145], v[194:197], v[118:121]
	v_mfma_f32_16x16x32_bf16 v[106:109], v[178:181], v[194:197], v[106:109]
	v_mfma_f32_16x16x32_bf16 v[98:101], v[142:145], v[202:205], v[98:101]
	v_mfma_f32_16x16x32_bf16 v[94:97], v[178:181], v[202:205], v[94:97]
	v_mfma_f32_16x16x32_bf16 v[86:89], v[142:145], v[210:213], v[86:89]
	v_mfma_f32_16x16x32_bf16 v[78:81], v[178:181], v[210:213], v[78:81]
	s_setprio 0
	s_barrier
	s_mov_b32 m0, s46
	v_lshl_add_u64 v[230:231], v[230:231], 0, s[8:9]
	ds_read_b128 v[214:217], v169
	ds_read_b128 v[218:221], v170
	ds_read_b128 v[222:225], v171
	ds_read_b128 v[226:229], v172
	global_load_lds_dwordx4 v[230:231], off
	v_lshl_add_u64 v[230:231], v[232:233], 0, s[8:9]
	s_mov_b32 m0, s47
	s_nop 0
	global_load_lds_dwordx4 v[230:231], off
	s_barrier
	s_waitcnt lgkmcnt(0)
	s_setprio 1
	s_waitcnt lgkmcnt(0)
	v_mfma_f32_16x16x32_bf16 v[114:117], v[214:217], v[182:185], v[114:117]
	v_mfma_f32_16x16x32_bf16 v[110:113], v[222:225], v[182:185], v[110:113]
	v_mfma_f32_16x16x32_bf16 v[102:105], v[214:217], v[190:193], v[102:105]
	v_mfma_f32_16x16x32_bf16 v[90:93], v[222:225], v[190:193], v[90:93]
	v_mfma_f32_16x16x32_bf16 v[82:85], v[214:217], v[198:201], v[82:85]
	v_mfma_f32_16x16x32_bf16 v[70:73], v[222:225], v[198:201], v[70:73]
	v_mfma_f32_16x16x32_bf16 v[74:77], v[214:217], v[206:209], v[74:77]
	v_mfma_f32_16x16x32_bf16 v[66:69], v[222:225], v[206:209], v[66:69]
	v_mfma_f32_16x16x32_bf16 v[114:117], v[218:221], v[186:189], v[114:117]
	v_mfma_f32_16x16x32_bf16 v[110:113], v[226:229], v[186:189], v[110:113]
	v_mfma_f32_16x16x32_bf16 v[102:105], v[218:221], v[194:197], v[102:105]
	v_mfma_f32_16x16x32_bf16 v[90:93], v[226:229], v[194:197], v[90:93]
	v_mfma_f32_16x16x32_bf16 v[82:85], v[218:221], v[202:205], v[82:85]
	v_mfma_f32_16x16x32_bf16 v[70:73], v[226:229], v[202:205], v[70:73]
	v_mfma_f32_16x16x32_bf16 v[74:77], v[218:221], v[210:213], v[74:77]
	v_mfma_f32_16x16x32_bf16 v[66:69], v[226:229], v[210:213], v[66:69]
	s_setprio 0
	s_mov_b32 m0, s48
	v_lshl_add_u64 v[230:231], v[234:235], 0, s[8:9]
	s_barrier
	ds_read_b128 v[182:185], v155 offset:49152
	ds_read_b128 v[186:189], v155 offset:50176
	ds_read_b128 v[190:193], v155 offset:51200
	ds_read_b128 v[194:197], v155 offset:52224
	ds_read_b128 v[198:201], v155 offset:53248
	ds_read_b128 v[202:205], v155 offset:54272
	ds_read_b128 v[206:209], v155 offset:55296
	ds_read_b128 v[210:213], v155 offset:56320
	global_load_lds_dwordx4 v[230:231], off
	v_lshl_add_u64 v[230:231], v[236:237], 0, s[8:9]
	s_mov_b32 m0, s49
	s_nop 0
	global_load_lds_dwordx4 v[230:231], off
	s_barrier
; __device__ __forceinline__ float bflo(uint32_t v) { return __uint_as_float(v << 16); }
; __device__ __forceinline__ float bfhi(uint32_t v) { return __uint_as_float(v & 0xFFFF0000u); }
; #define PG8_STAGE(bufoff, gbase, voff) do { _Pragma("unroll") for (int _i = 0; _i < 2; ++_i) \
;         __builtin_amdgcn_global_load_lds((const unsigned*)((const char*)(gbase) + (voff)[_i]), (PG8_LAS unsigned*)(lds + (bufoff) + ldsw + _i * 8192), 16, 0, 0); } while (0)
; #define PG8_WAIT_V(n) asm volatile("s_waitcnt vmcnt(" #n ")" ::: "memory")
; #define PG8_WAIT_L(n) asm volatile("s_waitcnt lgkmcnt(" #n ")" ::: "memory")
; #define PG8_BAR __builtin_amdgcn_s_barrier()
; template <class Epi, class Sched>
; __device__ __forceinline__ void gemm_phase(PG8_LAS unsigned char* lds, const Gemm g, const Sched& S, const Epi& E) {
;     ...
;             PG8_WAIT_V(6); PG8_BAR; PG8_MMA(1, 1, At, B1); PG8_BAR;
;             PG8_LDB(B0, 1, 0); PG8_SCHED; PG8_LDA(At, 1, 0); PG8_STAGE(PG8_SA(0, 1), a2 + hstep, voffA);
;             PG8_WAIT_L(8); PG8_BAR; PG8_WAIT_L(0); PG8_MMA(0, 0, At, B0); PG8_BAR; PG8_SCHED;
;             PG8_LDB(B1, 1, 1); PG8_STAGE(PG8_SB(1, 0), b3, voffB);
;             PG8_BAR; PG8_WAIT_L(0); PG8_MMA(0, 1, At, B1); PG8_BAR;
;             PG8_LDA(At, 1, 1); PG8_STAGE(PG8_SA(1, 0), a3, voffA);
;             PG8_BAR; PG8_WAIT_L(0); PG8_MMA(1, 0, At, B0); PG8_BAR; PG8_SCHED;
;             PG8_STAGE(PG8_SB(1, 1), b3 + hstep, voffB);
;             PG8_WAIT_V(6); PG8_BAR; PG8_MMA(1, 1, At, B1); PG8_BAR;
;   __device__ __forceinline__ void operator()(const acc8_t& acc, const pg8::Unit& u, int wr, int wc, int fr, int fq) const {
;     const u16* GA = (const u16*)(ws + OFF_GA); u16* M = (u16*)(ws + OFF_M);
; #pragma unroll
;     for (int ai = 0; ai < 2; ai++)
; #pragma unroll
;       for (int m = 0; m < 4; m++) {
;         const size_t token = EPI_TOKEN(u, ai, m);
; #pragma unroll
;         for (int bj = 0; bj < 2; bj++)
; #pragma unroll
;           for (int n = 0; n < 2; n++) {
;             const int f = EPI_COL(u, bj, n);
;             const uint2 ga = *(const uint2*)(GA + token * 1024 + f);
;             uint2 o;
;             o.x = pack2(bflo(ga.x) * acc[ai][bj][m][n][0], bfhi(ga.x) * acc[ai][bj][m][n][1]);
;             o.y = pack2(bflo(ga.y) * acc[ai][bj][m][n][2], bfhi(ga.y) * acc[ai][bj][m][n][3]);
;             *(uint2*)(M + token * 1024 + f) = o;
;           }
	s_waitcnt lgkmcnt(0)
	s_setprio 1
	s_waitcnt lgkmcnt(0)
	v_mfma_f32_16x16x32_bf16 v[62:65], v[138:141], v[182:185], v[62:65]
	v_mfma_f32_16x16x32_bf16 v[58:61], v[174:177], v[182:185], v[58:61]
	v_mfma_f32_16x16x32_bf16 v[50:53], v[138:141], v[190:193], v[50:53]
	v_mfma_f32_16x16x32_bf16 v[42:45], v[174:177], v[190:193], v[42:45]
	v_mfma_f32_16x16x32_bf16 v[30:33], v[138:141], v[198:201], v[30:33]
	v_mfma_f32_16x16x32_bf16 v[26:29], v[174:177], v[198:201], v[26:29]
	v_mfma_f32_16x16x32_bf16 v[14:17], v[138:141], v[206:209], v[14:17]
	v_mfma_f32_16x16x32_bf16 v[10:13], v[174:177], v[206:209], v[10:13]
	v_mfma_f32_16x16x32_bf16 v[62:65], v[142:145], v[186:189], v[62:65]
	v_mfma_f32_16x16x32_bf16 v[58:61], v[178:181], v[186:189], v[58:61]
	v_mfma_f32_16x16x32_bf16 v[50:53], v[142:145], v[194:197], v[50:53]
	v_mfma_f32_16x16x32_bf16 v[42:45], v[178:181], v[194:197], v[42:45]
	v_mfma_f32_16x16x32_bf16 v[30:33], v[142:145], v[202:205], v[30:33]
	v_mfma_f32_16x16x32_bf16 v[26:29], v[178:181], v[202:205], v[26:29]
	v_mfma_f32_16x16x32_bf16 v[14:17], v[142:145], v[210:213], v[14:17]
	v_mfma_f32_16x16x32_bf16 v[10:13], v[178:181], v[210:213], v[10:13]
	s_setprio 0
	s_barrier
	s_add_u32 s30, s30, 0x20080
	s_addc_u32 s31, s31, 0
	s_mov_b32 m0, s50
	v_lshl_add_u64 v[138:139], s[30:31], 0, v[130:131]
	global_load_lds_dwordx4 v[138:139], off
	v_lshl_add_u64 v[138:139], s[30:31], 0, v[132:133]
	s_mov_b32 m0, s51
	s_nop 0
	global_load_lds_dwordx4 v[138:139], off
	s_waitcnt vmcnt(6)
	s_barrier
	s_setprio 1
	v_mfma_f32_16x16x32_bf16 v[54:57], v[214:217], v[182:185], v[54:57]
	v_mfma_f32_16x16x32_bf16 v[46:49], v[222:225], v[182:185], v[46:49]
	v_mfma_f32_16x16x32_bf16 v[38:41], v[214:217], v[190:193], v[38:41]
	v_mfma_f32_16x16x32_bf16 v[34:37], v[222:225], v[190:193], v[34:37]
	v_mfma_f32_16x16x32_bf16 v[22:25], v[214:217], v[198:201], v[22:25]
	v_mfma_f32_16x16x32_bf16 v[18:21], v[222:225], v[198:201], v[18:21]
	v_mfma_f32_16x16x32_bf16 v[6:9], v[214:217], v[206:209], v[6:9]
	v_mfma_f32_16x16x32_bf16 v[2:5], v[222:225], v[206:209], v[2:5]
	v_mfma_f32_16x16x32_bf16 v[54:57], v[218:221], v[186:189], v[54:57]
	v_mfma_f32_16x16x32_bf16 v[46:49], v[226:229], v[186:189], v[46:49]
	v_mfma_f32_16x16x32_bf16 v[38:41], v[218:221], v[194:197], v[38:41]
	v_mfma_f32_16x16x32_bf16 v[34:37], v[226:229], v[194:197], v[34:37]
	v_mfma_f32_16x16x32_bf16 v[22:25], v[218:221], v[202:205], v[22:25]
	v_mfma_f32_16x16x32_bf16 v[18:21], v[226:229], v[202:205], v[18:21]
	v_mfma_f32_16x16x32_bf16 v[6:9], v[218:221], v[210:213], v[6:9]
	v_mfma_f32_16x16x32_bf16 v[2:5], v[226:229], v[210:213], v[2:5]
	s_setprio 0
	s_add_i32 s63, s63, 2
	s_add_u32 s28, s28, 0x100
	s_addc_u32 s29, s29, 0
	s_add_u32 s61, s61, 0x100
	s_addc_u32 s62, s62, 0
	s_cmp_gt_u32 s63, 5
	s_barrier
	s_cbranch_scc0 .LBB0_694
	v_lshl_add_u32 v138, s26, 8, v154
	v_lshl_or_b32 v140, s24, 8, v156
	v_ashrrev_i32_e32 v139, 31, v138
	v_ashrrev_i32_e32 v141, 31, v140
	v_lshlrev_b64 v[142:143], 11, v[138:139]
	v_lshlrev_b64 v[140:141], 1, v[140:141]
	v_bfe_u32 v144, v0, 4, 1
	v_mov_b32_e32 v145, 0
	v_mul_u32_u24_e32 v144, 24, v144
	v_lshl_add_u64 v[142:143], v[142:143], 0, v[140:141]
	v_lshl_add_u64 v[142:143], v[142:143], 0, v[144:145]
	v_lshl_add_u64 v[232:233], s[10:11], 0, v[142:143]
	v_lshl_add_u64 v[236:237], s[12:13], 0, v[142:143]
	s_mov_b32 s24, s14
	s_mov_b32 s26, s16
	s_mov_b64 s[30:31], s[22:23]
	s_mov_b64 s[28:29], s[20:21]
	global_load_dwordx4 v[176:179], v[232:233], off nt
	global_load_dwordx4 v[180:183], v[232:233], off offset:256 nt
	v_permlane16_swap_b32_e32 v126, v122
	v_permlane16_swap_b32_e32 v127, v123
	v_permlane16_swap_b32_e32 v128, v124
	v_permlane16_swap_b32_e32 v129, v125
	v_permlane16_swap_b32_e32 v114, v110
	v_permlane16_swap_b32_e32 v115, v111
	v_permlane16_swap_b32_e32 v116, v112
	v_permlane16_swap_b32_e32 v117, v113
	s_mov_b64 s[4:5], 0x8000
	v_lshl_add_u64 v[232:233], v[232:233], 0, s[4:5]
	global_load_dwordx4 v[192:195], v[232:233], off nt
	global_load_dwordx4 v[196:199], v[232:233], off offset:256 nt
	s_waitcnt vmcnt(2)
	v_lshlrev_b32_e32 v208, 16, v176
	v_and_b32_e32 v209, 0xffff0000, v176
	v_pk_mul_f32 v[126:127], v[126:127], v[208:209]
	v_lshlrev_b32_e32 v210, 16, v177
	v_and_b32_e32 v211, 0xffff0000, v177
	v_pk_mul_f32 v[128:129], v[128:129], v[210:211]
	v_lshlrev_b32_e32 v212, 16, v178
	v_and_b32_e32 v213, 0xffff0000, v178
	v_pk_mul_f32 v[122:123], v[122:123], v[212:213]
	v_lshlrev_b32_e32 v214, 16, v179
	v_and_b32_e32 v215, 0xffff0000, v179
	v_pk_mul_f32 v[124:125], v[124:125], v[214:215]
	v_cvt_pk_bf16_f32 v224, v126, v127
	v_cvt_pk_bf16_f32 v225, v128, v129
	v_cvt_pk_bf16_f32 v226, v122, v123
	v_cvt_pk_bf16_f32 v227, v124, v125
	v_lshlrev_b32_e32 v208, 16, v180
	v_and_b32_e32 v209, 0xffff0000, v180
	v_pk_mul_f32 v[114:115], v[114:115], v[208:209]
	v_lshlrev_b32_e32 v210, 16, v181
	v_and_b32_e32 v211, 0xffff0000, v181
	v_pk_mul_f32 v[116:117], v[116:117], v[210:211]
	v_lshlrev_b32_e32 v212, 16, v182
	v_and_b32_e32 v213, 0xffff0000, v182
	v_pk_mul_f32 v[110:111], v[110:111], v[212:213]
	v_lshlrev_b32_e32 v214, 16, v183
	v_and_b32_e32 v215, 0xffff0000, v183
	v_pk_mul_f32 v[112:113], v[112:113], v[214:215]
	v_cvt_pk_bf16_f32 v228, v114, v115
	v_cvt_pk_bf16_f32 v229, v116, v117
	v_cvt_pk_bf16_f32 v230, v110, v111
	v_cvt_pk_bf16_f32 v231, v112, v113
	global_store_dwordx4 v[236:237], v[224:227], off
	global_store_dwordx4 v[236:237], v[228:231], off offset:256
	v_lshl_add_u64 v[236:237], v[236:237], 0, s[4:5]
	v_permlane16_swap_b32_e32 v118, v106
	v_permlane16_swap_b32_e32 v119, v107
	v_permlane16_swap_b32_e32 v120, v108
	v_permlane16_swap_b32_e32 v121, v109
	v_permlane16_swap_b32_e32 v102, v90
	v_permlane16_swap_b32_e32 v103, v91
	v_permlane16_swap_b32_e32 v104, v92
	v_permlane16_swap_b32_e32 v105, v93
	s_mov_b64 s[4:5], 0x8000
	v_lshl_add_u64 v[232:233], v[232:233], 0, s[4:5]
	global_load_dwordx4 v[176:179], v[232:233], off nt
	global_load_dwordx4 v[180:183], v[232:233], off offset:256 nt
	s_waitcnt vmcnt(4)
; __device__ __forceinline__ float bflo(uint32_t v) { return __uint_as_float(v << 16); }
; __device__ __forceinline__ float bfhi(uint32_t v) { return __uint_as_float(v & 0xFFFF0000u); }
;   __device__ __forceinline__ void operator()(const acc8_t& acc, const pg8::Unit& u, int wr, int wc, int fr, int fq) const {
;     ...
;     for (int ai = 0; ai < 2; ai++)
; #pragma unroll
;       for (int m = 0; m < 4; m++) {
;         const size_t token = EPI_TOKEN(u, ai, m);
; #pragma unroll
;         for (int bj = 0; bj < 2; bj++)
; #pragma unroll
;           for (int n = 0; n < 2; n++) {
;             const int f = EPI_COL(u, bj, n);
;             const uint2 ga = *(const uint2*)(GA + token * 1024 + f);
;             uint2 o;
;             o.x = pack2(bflo(ga.x) * acc[ai][bj][m][n][0], bfhi(ga.x) * acc[ai][bj][m][n][1]);
;             o.y = pack2(bflo(ga.y) * acc[ai][bj][m][n][2], bfhi(ga.y) * acc[ai][bj][m][n][3]);
;             *(uint2*)(M + token * 1024 + f) = o;
;           }
	v_lshlrev_b32_e32 v208, 16, v192
	v_and_b32_e32 v209, 0xffff0000, v192
	v_pk_mul_f32 v[118:119], v[118:119], v[208:209]
	v_lshlrev_b32_e32 v210, 16, v193
	v_and_b32_e32 v211, 0xffff0000, v193
	v_pk_mul_f32 v[120:121], v[120:121], v[210:211]
	v_lshlrev_b32_e32 v212, 16, v194
	v_and_b32_e32 v213, 0xffff0000, v194
	v_pk_mul_f32 v[106:107], v[106:107], v[212:213]
	v_lshlrev_b32_e32 v214, 16, v195
	v_and_b32_e32 v215, 0xffff0000, v195
	v_pk_mul_f32 v[108:109], v[108:109], v[214:215]
	v_cvt_pk_bf16_f32 v224, v118, v119
	v_cvt_pk_bf16_f32 v225, v120, v121
	v_cvt_pk_bf16_f32 v226, v106, v107
	v_cvt_pk_bf16_f32 v227, v108, v109
	v_lshlrev_b32_e32 v208, 16, v196
	v_and_b32_e32 v209, 0xffff0000, v196
	v_pk_mul_f32 v[102:103], v[102:103], v[208:209]
	v_lshlrev_b32_e32 v210, 16, v197
	v_and_b32_e32 v211, 0xffff0000, v197
	v_pk_mul_f32 v[104:105], v[104:105], v[210:211]
	v_lshlrev_b32_e32 v212, 16, v198
	v_and_b32_e32 v213, 0xffff0000, v198
	v_pk_mul_f32 v[90:91], v[90:91], v[212:213]
	v_lshlrev_b32_e32 v214, 16, v199
	v_and_b32_e32 v215, 0xffff0000, v199
	v_pk_mul_f32 v[92:93], v[92:93], v[214:215]
	v_cvt_pk_bf16_f32 v228, v102, v103
	v_cvt_pk_bf16_f32 v229, v104, v105
	v_cvt_pk_bf16_f32 v230, v90, v91
	v_cvt_pk_bf16_f32 v231, v92, v93
	global_store_dwordx4 v[236:237], v[224:227], off
	global_store_dwordx4 v[236:237], v[228:231], off offset:256
	v_lshl_add_u64 v[236:237], v[236:237], 0, s[4:5]
	v_permlane16_swap_b32_e32 v98, v94
	v_permlane16_swap_b32_e32 v99, v95
	v_permlane16_swap_b32_e32 v100, v96
	v_permlane16_swap_b32_e32 v101, v97
	v_permlane16_swap_b32_e32 v82, v70
	v_permlane16_swap_b32_e32 v83, v71
	v_permlane16_swap_b32_e32 v84, v72
	v_permlane16_swap_b32_e32 v85, v73
	s_mov_b64 s[4:5], 0x8000
	v_lshl_add_u64 v[232:233], v[232:233], 0, s[4:5]
	global_load_dwordx4 v[192:195], v[232:233], off nt
	global_load_dwordx4 v[196:199], v[232:233], off offset:256 nt
	s_waitcnt vmcnt(4)
	v_lshlrev_b32_e32 v208, 16, v176
	v_and_b32_e32 v209, 0xffff0000, v176
	v_pk_mul_f32 v[98:99], v[98:99], v[208:209]
	v_lshlrev_b32_e32 v210, 16, v177
	v_and_b32_e32 v211, 0xffff0000, v177
	v_pk_mul_f32 v[100:101], v[100:101], v[210:211]
	v_lshlrev_b32_e32 v212, 16, v178
	v_and_b32_e32 v213, 0xffff0000, v178
	v_pk_mul_f32 v[94:95], v[94:95], v[212:213]
	v_lshlrev_b32_e32 v214, 16, v179
	v_and_b32_e32 v215, 0xffff0000, v179
	v_pk_mul_f32 v[96:97], v[96:97], v[214:215]
	v_cvt_pk_bf16_f32 v224, v98, v99
	v_cvt_pk_bf16_f32 v225, v100, v101
	v_cvt_pk_bf16_f32 v226, v94, v95
	v_cvt_pk_bf16_f32 v227, v96, v97
	v_lshlrev_b32_e32 v208, 16, v180
	v_and_b32_e32 v209, 0xffff0000, v180
	v_pk_mul_f32 v[82:83], v[82:83], v[208:209]
	v_lshlrev_b32_e32 v210, 16, v181
	v_and_b32_e32 v211, 0xffff0000, v181
	v_pk_mul_f32 v[84:85], v[84:85], v[210:211]
	v_lshlrev_b32_e32 v212, 16, v182
	v_and_b32_e32 v213, 0xffff0000, v182
	v_pk_mul_f32 v[70:71], v[70:71], v[212:213]
	v_lshlrev_b32_e32 v214, 16, v183
	v_and_b32_e32 v215, 0xffff0000, v183
	v_pk_mul_f32 v[72:73], v[72:73], v[214:215]
	v_cvt_pk_bf16_f32 v228, v82, v83
	v_cvt_pk_bf16_f32 v229, v84, v85
	v_cvt_pk_bf16_f32 v230, v70, v71
	v_cvt_pk_bf16_f32 v231, v72, v73
	global_store_dwordx4 v[236:237], v[224:227], off
	global_store_dwordx4 v[236:237], v[228:231], off offset:256
	v_lshl_add_u64 v[236:237], v[236:237], 0, s[4:5]
	v_permlane16_swap_b32_e32 v86, v78
	v_permlane16_swap_b32_e32 v87, v79
	v_permlane16_swap_b32_e32 v88, v80
	v_permlane16_swap_b32_e32 v89, v81
	v_permlane16_swap_b32_e32 v74, v66
	v_permlane16_swap_b32_e32 v75, v67
	v_permlane16_swap_b32_e32 v76, v68
	v_permlane16_swap_b32_e32 v77, v69
	s_mov_b64 s[4:5], 0x28000
	v_lshl_add_u64 v[232:233], v[232:233], 0, s[4:5]
	global_load_dwordx4 v[176:179], v[232:233], off nt
	global_load_dwordx4 v[180:183], v[232:233], off offset:256 nt
	s_waitcnt vmcnt(4)
	v_lshlrev_b32_e32 v208, 16, v192
	v_and_b32_e32 v209, 0xffff0000, v192
	v_pk_mul_f32 v[86:87], v[86:87], v[208:209]
	v_lshlrev_b32_e32 v210, 16, v193
	v_and_b32_e32 v211, 0xffff0000, v193
	v_pk_mul_f32 v[88:89], v[88:89], v[210:211]
	v_lshlrev_b32_e32 v212, 16, v194
	v_and_b32_e32 v213, 0xffff0000, v194
	v_pk_mul_f32 v[78:79], v[78:79], v[212:213]
	v_lshlrev_b32_e32 v214, 16, v195
	v_and_b32_e32 v215, 0xffff0000, v195
	v_pk_mul_f32 v[80:81], v[80:81], v[214:215]
	v_cvt_pk_bf16_f32 v224, v86, v87
	v_cvt_pk_bf16_f32 v225, v88, v89
	v_cvt_pk_bf16_f32 v226, v78, v79
	v_cvt_pk_bf16_f32 v227, v80, v81
	v_lshlrev_b32_e32 v208, 16, v196
	v_and_b32_e32 v209, 0xffff0000, v196
	v_pk_mul_f32 v[74:75], v[74:75], v[208:209]
	v_lshlrev_b32_e32 v210, 16, v197
	v_and_b32_e32 v211, 0xffff0000, v197
	v_pk_mul_f32 v[76:77], v[76:77], v[210:211]
	v_lshlrev_b32_e32 v212, 16, v198
	v_and_b32_e32 v213, 0xffff0000, v198
	v_pk_mul_f32 v[66:67], v[66:67], v[212:213]
	v_lshlrev_b32_e32 v214, 16, v199
	v_and_b32_e32 v215, 0xffff0000, v199
	v_pk_mul_f32 v[68:69], v[68:69], v[214:215]
	v_cvt_pk_bf16_f32 v228, v74, v75
	v_cvt_pk_bf16_f32 v229, v76, v77
	v_cvt_pk_bf16_f32 v230, v66, v67
	v_cvt_pk_bf16_f32 v231, v68, v69
	global_store_dwordx4 v[236:237], v[224:227], off
	global_store_dwordx4 v[236:237], v[228:231], off offset:256
	v_lshl_add_u64 v[236:237], v[236:237], 0, s[4:5]
	v_permlane16_swap_b32_e32 v62, v58
	v_permlane16_swap_b32_e32 v63, v59
	v_permlane16_swap_b32_e32 v64, v60
	v_permlane16_swap_b32_e32 v65, v61
	v_permlane16_swap_b32_e32 v54, v46
	v_permlane16_swap_b32_e32 v55, v47
	v_permlane16_swap_b32_e32 v56, v48
	v_permlane16_swap_b32_e32 v57, v49
	s_mov_b64 s[4:5], 0x8000
	v_lshl_add_u64 v[232:233], v[232:233], 0, s[4:5]
	global_load_dwordx4 v[192:195], v[232:233], off nt
	global_load_dwordx4 v[196:199], v[232:233], off offset:256 nt
	s_waitcnt vmcnt(4)
; __device__ __forceinline__ float bflo(uint32_t v) { return __uint_as_float(v << 16); }
; __device__ __forceinline__ float bfhi(uint32_t v) { return __uint_as_float(v & 0xFFFF0000u); }
; #define PG8_WAIT_V(n) asm volatile("s_waitcnt vmcnt(" #n ")" ::: "memory")
; #define PG8_BAR __builtin_amdgcn_s_barrier()
; template <class Epi, class Sched>
; __device__ __forceinline__ void gemm_phase(PG8_LAS unsigned char* lds, const Gemm g, const Sched& S, const Epi& E) {
;     ...
;         E(acc, cur, wr, wc, fr, fq);
;         if (!has_next) break;
; #pragma unroll
;         for (int a = 0; a < 2; ++a)
; #pragma unroll
;             for (int b = 0; b < 2; ++b)
; #pragma unroll
;                 for (int m = 0; m < 4; ++m)
; #pragma unroll
;                     for (int n = 0; n < 2; ++n) acc[a][b][m][n] = (f32x4){0.f, 0.f, 0.f, 0.f};
;         cur = nxt; cA = nA; cB = nB; ++ui;
;     }
;     PG8_WAIT_V(0);
;     if (wr == 0) PG8_BAR;
;     PG8_BAR;
;   __device__ __forceinline__ void operator()(const acc8_t& acc, const pg8::Unit& u, int wr, int wc, int fr, int fq) const {
;     ...
;     for (int ai = 0; ai < 2; ai++)
; #pragma unroll
;       for (int m = 0; m < 4; m++) {
;         const size_t token = EPI_TOKEN(u, ai, m);
; #pragma unroll
;         for (int bj = 0; bj < 2; bj++)
; #pragma unroll
;           for (int n = 0; n < 2; n++) {
;             const int f = EPI_COL(u, bj, n);
;             const uint2 ga = *(const uint2*)(GA + token * 1024 + f);
;             uint2 o;
;             o.x = pack2(bflo(ga.x) * acc[ai][bj][m][n][0], bfhi(ga.x) * acc[ai][bj][m][n][1]);
;             o.y = pack2(bflo(ga.y) * acc[ai][bj][m][n][2], bfhi(ga.y) * acc[ai][bj][m][n][3]);
;             *(uint2*)(M + token * 1024 + f) = o;
;           }
	v_lshlrev_b32_e32 v208, 16, v176
	v_and_b32_e32 v209, 0xffff0000, v176
	v_pk_mul_f32 v[62:63], v[62:63], v[208:209]
	v_lshlrev_b32_e32 v210, 16, v177
	v_and_b32_e32 v211, 0xffff0000, v177
	v_pk_mul_f32 v[64:65], v[64:65], v[210:211]
	v_lshlrev_b32_e32 v212, 16, v178
	v_and_b32_e32 v213, 0xffff0000, v178
	v_pk_mul_f32 v[58:59], v[58:59], v[212:213]
	v_lshlrev_b32_e32 v214, 16, v179
	v_and_b32_e32 v215, 0xffff0000, v179
	v_pk_mul_f32 v[60:61], v[60:61], v[214:215]
	v_cvt_pk_bf16_f32 v224, v62, v63
	v_cvt_pk_bf16_f32 v225, v64, v65
	v_cvt_pk_bf16_f32 v226, v58, v59
	v_cvt_pk_bf16_f32 v227, v60, v61
	v_lshlrev_b32_e32 v208, 16, v180
	v_and_b32_e32 v209, 0xffff0000, v180
	v_pk_mul_f32 v[54:55], v[54:55], v[208:209]
	v_lshlrev_b32_e32 v210, 16, v181
	v_and_b32_e32 v211, 0xffff0000, v181
	v_pk_mul_f32 v[56:57], v[56:57], v[210:211]
	v_lshlrev_b32_e32 v212, 16, v182
	v_and_b32_e32 v213, 0xffff0000, v182
	v_pk_mul_f32 v[46:47], v[46:47], v[212:213]
	v_lshlrev_b32_e32 v214, 16, v183
	v_and_b32_e32 v215, 0xffff0000, v183
	v_pk_mul_f32 v[48:49], v[48:49], v[214:215]
	v_cvt_pk_bf16_f32 v228, v54, v55
	v_cvt_pk_bf16_f32 v229, v56, v57
	v_cvt_pk_bf16_f32 v230, v46, v47
	v_cvt_pk_bf16_f32 v231, v48, v49
	global_store_dwordx4 v[236:237], v[224:227], off
	global_store_dwordx4 v[236:237], v[228:231], off offset:256
	v_lshl_add_u64 v[236:237], v[236:237], 0, s[4:5]
	v_permlane16_swap_b32_e32 v50, v42
	v_permlane16_swap_b32_e32 v51, v43
	v_permlane16_swap_b32_e32 v52, v44
	v_permlane16_swap_b32_e32 v53, v45
	v_permlane16_swap_b32_e32 v38, v34
	v_permlane16_swap_b32_e32 v39, v35
	v_permlane16_swap_b32_e32 v40, v36
	v_permlane16_swap_b32_e32 v41, v37
	s_mov_b64 s[4:5], 0x8000
	v_lshl_add_u64 v[232:233], v[232:233], 0, s[4:5]
	global_load_dwordx4 v[176:179], v[232:233], off nt
	global_load_dwordx4 v[180:183], v[232:233], off offset:256 nt
	s_waitcnt vmcnt(4)
	v_lshlrev_b32_e32 v208, 16, v192
	v_and_b32_e32 v209, 0xffff0000, v192
	v_pk_mul_f32 v[50:51], v[50:51], v[208:209]
	v_lshlrev_b32_e32 v210, 16, v193
	v_and_b32_e32 v211, 0xffff0000, v193
	v_pk_mul_f32 v[52:53], v[52:53], v[210:211]
	v_lshlrev_b32_e32 v212, 16, v194
	v_and_b32_e32 v213, 0xffff0000, v194
	v_pk_mul_f32 v[42:43], v[42:43], v[212:213]
	v_lshlrev_b32_e32 v214, 16, v195
	v_and_b32_e32 v215, 0xffff0000, v195
	v_pk_mul_f32 v[44:45], v[44:45], v[214:215]
	v_cvt_pk_bf16_f32 v224, v50, v51
	v_cvt_pk_bf16_f32 v225, v52, v53
	v_cvt_pk_bf16_f32 v226, v42, v43
	v_cvt_pk_bf16_f32 v227, v44, v45
	v_lshlrev_b32_e32 v208, 16, v196
	v_and_b32_e32 v209, 0xffff0000, v196
	v_pk_mul_f32 v[38:39], v[38:39], v[208:209]
	v_lshlrev_b32_e32 v210, 16, v197
	v_and_b32_e32 v211, 0xffff0000, v197
	v_pk_mul_f32 v[40:41], v[40:41], v[210:211]
	v_lshlrev_b32_e32 v212, 16, v198
	v_and_b32_e32 v213, 0xffff0000, v198
	v_pk_mul_f32 v[34:35], v[34:35], v[212:213]
	v_lshlrev_b32_e32 v214, 16, v199
	v_and_b32_e32 v215, 0xffff0000, v199
	v_pk_mul_f32 v[36:37], v[36:37], v[214:215]
	v_cvt_pk_bf16_f32 v228, v38, v39
	v_cvt_pk_bf16_f32 v229, v40, v41
	v_cvt_pk_bf16_f32 v230, v34, v35
	v_cvt_pk_bf16_f32 v231, v36, v37
	global_store_dwordx4 v[236:237], v[224:227], off
	global_store_dwordx4 v[236:237], v[228:231], off offset:256
	v_lshl_add_u64 v[236:237], v[236:237], 0, s[4:5]
	v_permlane16_swap_b32_e32 v30, v26
	v_permlane16_swap_b32_e32 v31, v27
	v_permlane16_swap_b32_e32 v32, v28
	v_permlane16_swap_b32_e32 v33, v29
	v_permlane16_swap_b32_e32 v22, v18
	v_permlane16_swap_b32_e32 v23, v19
	v_permlane16_swap_b32_e32 v24, v20
	v_permlane16_swap_b32_e32 v25, v21
	s_mov_b64 s[4:5], 0x8000
	v_lshl_add_u64 v[232:233], v[232:233], 0, s[4:5]
	global_load_dwordx4 v[192:195], v[232:233], off nt
	global_load_dwordx4 v[196:199], v[232:233], off offset:256 nt
	s_waitcnt vmcnt(4)
	v_lshlrev_b32_e32 v208, 16, v176
	v_and_b32_e32 v209, 0xffff0000, v176
	v_pk_mul_f32 v[30:31], v[30:31], v[208:209]
	v_lshlrev_b32_e32 v210, 16, v177
	v_and_b32_e32 v211, 0xffff0000, v177
	v_pk_mul_f32 v[32:33], v[32:33], v[210:211]
	v_lshlrev_b32_e32 v212, 16, v178
	v_and_b32_e32 v213, 0xffff0000, v178
	v_pk_mul_f32 v[26:27], v[26:27], v[212:213]
	v_lshlrev_b32_e32 v214, 16, v179
	v_and_b32_e32 v215, 0xffff0000, v179
	v_pk_mul_f32 v[28:29], v[28:29], v[214:215]
	v_cvt_pk_bf16_f32 v224, v30, v31
	v_cvt_pk_bf16_f32 v225, v32, v33
	v_cvt_pk_bf16_f32 v226, v26, v27
	v_cvt_pk_bf16_f32 v227, v28, v29
	v_lshlrev_b32_e32 v208, 16, v180
	v_and_b32_e32 v209, 0xffff0000, v180
	v_pk_mul_f32 v[22:23], v[22:23], v[208:209]
	v_lshlrev_b32_e32 v210, 16, v181
	v_and_b32_e32 v211, 0xffff0000, v181
	v_pk_mul_f32 v[24:25], v[24:25], v[210:211]
	v_lshlrev_b32_e32 v212, 16, v182
	v_and_b32_e32 v213, 0xffff0000, v182
	v_pk_mul_f32 v[18:19], v[18:19], v[212:213]
	v_lshlrev_b32_e32 v214, 16, v183
	v_and_b32_e32 v215, 0xffff0000, v183
	v_pk_mul_f32 v[20:21], v[20:21], v[214:215]
	v_cvt_pk_bf16_f32 v228, v22, v23
	v_cvt_pk_bf16_f32 v229, v24, v25
	v_cvt_pk_bf16_f32 v230, v18, v19
	v_cvt_pk_bf16_f32 v231, v20, v21
	global_store_dwordx4 v[236:237], v[224:227], off
	global_store_dwordx4 v[236:237], v[228:231], off offset:256
	v_lshl_add_u64 v[236:237], v[236:237], 0, s[4:5]
	v_permlane16_swap_b32_e32 v14, v10
	v_permlane16_swap_b32_e32 v15, v11
	v_permlane16_swap_b32_e32 v16, v12
	v_permlane16_swap_b32_e32 v17, v13
	v_permlane16_swap_b32_e32 v6, v2
	v_permlane16_swap_b32_e32 v7, v3
	v_permlane16_swap_b32_e32 v8, v4
	v_permlane16_swap_b32_e32 v9, v5
	s_waitcnt vmcnt(2)
	v_lshlrev_b32_e32 v208, 16, v192
	v_and_b32_e32 v209, 0xffff0000, v192
	v_pk_mul_f32 v[14:15], v[14:15], v[208:209]
	v_lshlrev_b32_e32 v210, 16, v193
	v_and_b32_e32 v211, 0xffff0000, v193
	v_pk_mul_f32 v[16:17], v[16:17], v[210:211]
	v_lshlrev_b32_e32 v212, 16, v194
	v_and_b32_e32 v213, 0xffff0000, v194
	v_pk_mul_f32 v[10:11], v[10:11], v[212:213]
	v_lshlrev_b32_e32 v214, 16, v195
	v_and_b32_e32 v215, 0xffff0000, v195
	v_pk_mul_f32 v[12:13], v[12:13], v[214:215]
	v_cvt_pk_bf16_f32 v224, v14, v15
	v_cvt_pk_bf16_f32 v225, v16, v17
	v_cvt_pk_bf16_f32 v226, v10, v11
	v_cvt_pk_bf16_f32 v227, v12, v13
	v_lshlrev_b32_e32 v208, 16, v196
	v_and_b32_e32 v209, 0xffff0000, v196
	v_pk_mul_f32 v[6:7], v[6:7], v[208:209]
	v_lshlrev_b32_e32 v210, 16, v197
	v_and_b32_e32 v211, 0xffff0000, v197
	v_pk_mul_f32 v[8:9], v[8:9], v[210:211]
	v_lshlrev_b32_e32 v212, 16, v198
	v_and_b32_e32 v213, 0xffff0000, v198
	v_pk_mul_f32 v[2:3], v[2:3], v[212:213]
	v_lshlrev_b32_e32 v214, 16, v199
	v_and_b32_e32 v215, 0xffff0000, v199
	v_pk_mul_f32 v[4:5], v[4:5], v[214:215]
	v_cvt_pk_bf16_f32 v228, v6, v7
	v_cvt_pk_bf16_f32 v229, v8, v9
	v_cvt_pk_bf16_f32 v230, v2, v3
	v_cvt_pk_bf16_f32 v231, v4, v5
	global_store_dwordx4 v[236:237], v[224:227], off
	global_store_dwordx4 v[236:237], v[228:231], off offset:256
	s_and_b64 vcc, exec, s[18:19]
	s_cbranch_vccz .LBB0_688
	s_waitcnt vmcnt(0)
	s_cmpk_gt_u32 s33, 0xff
	s_cbranch_scc1 .LBB0_698
	s_barrier

; __device__ __forceinline__ float bflo(uint32_t v) { return __uint_as_float(v << 16); }
; __device__ __forceinline__ float bfhi(uint32_t v) { return __uint_as_float(v & 0xFFFF0000u); }
;   __device__ __forceinline__ void operator()(const acc8_t& acc, const pg8::Unit& u, int wr, int wc, int fr, int fq) const {
;     const u16* GB = (const u16*)(ws + OFF_GB); u16* M = (u16*)(ws + OFF_M);
; #pragma unroll
;     for (int ai = 0; ai < 2; ai++)
; #pragma unroll
;       for (int m = 0; m < 4; m++) {
;         const size_t token = EPI_TOKEN(u, ai, m);
; #pragma unroll
;         for (int bj = 0; bj < 2; bj++)
; #pragma unroll
;           for (int n = 0; n < 2; n++) {
;             const int f = EPI_COL(u, bj, n);
;             const uint2 gb = *(const uint2*)(GB + token * 1024 + f);
;             const uint2 mo = *(const uint2*)(M + token * 1024 + f);
;             uint2 o;
;             o.x = pack2(bflo(mo.x) + bflo(gb.x) * acc[ai][bj][m][n][0], bfhi(mo.x) + bfhi(gb.x) * acc[ai][bj][m][n][1]);
;             o.y = pack2(bflo(mo.y) + bflo(gb.y) * acc[ai][bj][m][n][2], bfhi(mo.y) + bfhi(gb.y) * acc[ai][bj][m][n][3]);
;             *(uint2*)(M + token * 1024 + f) = o;
.Lp4r_go:
	v_lshl_add_u32 v138, s24, 8, v154
	v_lshl_or_b32 v140, s22, 8, v156
	v_ashrrev_i32_e32 v139, 31, v138
	v_ashrrev_i32_e32 v141, 31, v140
	v_lshlrev_b64 v[142:143], 11, v[138:139]
	v_lshlrev_b64 v[140:141], 1, v[140:141]
	v_bfe_u32 v144, v0, 4, 1
	v_mov_b32_e32 v145, 0
	v_mul_u32_u24_e32 v144, 24, v144
	v_lshl_add_u64 v[142:143], v[142:143], 0, v[140:141]
	v_lshl_add_u64 v[142:143], v[142:143], 0, v[144:145]
	v_lshl_add_u64 v[232:233], s[8:9], 0, v[142:143]
	v_lshl_add_u64 v[236:237], s[10:11], 0, v[142:143]
	v_lshl_add_u64 v[234:235], s[10:11], 0, v[142:143]
	s_mov_b32 s22, s12
	s_mov_b32 s24, s14
	s_mov_b64 s[28:29], s[20:21]
	s_mov_b64 s[26:27], s[18:19]
	global_load_dwordx4 v[176:179], v[232:233], off nt
	global_load_dwordx4 v[180:183], v[232:233], off offset:256 nt
	global_load_dwordx4 v[184:187], v[234:235], off
	global_load_dwordx4 v[188:191], v[234:235], off offset:256
	v_permlane16_swap_b32_e32 v126, v122
	v_permlane16_swap_b32_e32 v127, v123
	v_permlane16_swap_b32_e32 v128, v124
	v_permlane16_swap_b32_e32 v129, v125
	v_permlane16_swap_b32_e32 v118, v114
	v_permlane16_swap_b32_e32 v119, v115
	v_permlane16_swap_b32_e32 v120, v116
	v_permlane16_swap_b32_e32 v121, v117
	s_mov_b64 s[4:5], 0x8000
	v_lshl_add_u64 v[232:233], v[232:233], 0, s[4:5]
	v_lshl_add_u64 v[234:235], v[234:235], 0, s[4:5]
	global_load_dwordx4 v[192:195], v[232:233], off nt
	global_load_dwordx4 v[196:199], v[232:233], off offset:256 nt
	global_load_dwordx4 v[200:203], v[234:235], off
	global_load_dwordx4 v[204:207], v[234:235], off offset:256
	s_waitcnt vmcnt(4)
	v_lshlrev_b32_e32 v208, 16, v176
	v_and_b32_e32 v209, 0xffff0000, v176
	v_lshlrev_b32_e32 v216, 16, v184
	v_and_b32_e32 v217, 0xffff0000, v184
	v_pk_fma_f32 v[126:127], v[126:127], v[208:209], v[216:217]
	v_lshlrev_b32_e32 v210, 16, v177
	v_and_b32_e32 v211, 0xffff0000, v177
	v_lshlrev_b32_e32 v218, 16, v185
	v_and_b32_e32 v219, 0xffff0000, v185
	v_pk_fma_f32 v[128:129], v[128:129], v[210:211], v[218:219]
	v_lshlrev_b32_e32 v212, 16, v178
	v_and_b32_e32 v213, 0xffff0000, v178
	v_lshlrev_b32_e32 v220, 16, v186
	v_and_b32_e32 v221, 0xffff0000, v186
	v_pk_fma_f32 v[122:123], v[122:123], v[212:213], v[220:221]
	v_lshlrev_b32_e32 v214, 16, v179
	v_and_b32_e32 v215, 0xffff0000, v179
	v_lshlrev_b32_e32 v222, 16, v187
	v_and_b32_e32 v223, 0xffff0000, v187
	v_pk_fma_f32 v[124:125], v[124:125], v[214:215], v[222:223]
	v_cvt_pk_bf16_f32 v224, v126, v127
	v_cvt_pk_bf16_f32 v225, v128, v129
	v_cvt_pk_bf16_f32 v226, v122, v123
	v_cvt_pk_bf16_f32 v227, v124, v125
	v_lshlrev_b32_e32 v208, 16, v180
	v_and_b32_e32 v209, 0xffff0000, v180
	v_lshlrev_b32_e32 v216, 16, v188
	v_and_b32_e32 v217, 0xffff0000, v188
	v_pk_fma_f32 v[118:119], v[118:119], v[208:209], v[216:217]
	v_lshlrev_b32_e32 v210, 16, v181
	v_and_b32_e32 v211, 0xffff0000, v181
	v_lshlrev_b32_e32 v218, 16, v189
	v_and_b32_e32 v219, 0xffff0000, v189
	v_pk_fma_f32 v[120:121], v[120:121], v[210:211], v[218:219]
	v_lshlrev_b32_e32 v212, 16, v182
	v_and_b32_e32 v213, 0xffff0000, v182
	v_lshlrev_b32_e32 v220, 16, v190
	v_and_b32_e32 v221, 0xffff0000, v190
	v_pk_fma_f32 v[114:115], v[114:115], v[212:213], v[220:221]
	v_lshlrev_b32_e32 v214, 16, v183
	v_and_b32_e32 v215, 0xffff0000, v183
	v_lshlrev_b32_e32 v222, 16, v191
	v_and_b32_e32 v223, 0xffff0000, v191
	v_pk_fma_f32 v[116:117], v[116:117], v[214:215], v[222:223]
	v_cvt_pk_bf16_f32 v228, v118, v119
	v_cvt_pk_bf16_f32 v229, v120, v121
	v_cvt_pk_bf16_f32 v230, v114, v115
	v_cvt_pk_bf16_f32 v231, v116, v117
	global_store_dwordx4 v[236:237], v[224:227], off
	global_store_dwordx4 v[236:237], v[228:231], off offset:256
	v_lshl_add_u64 v[236:237], v[236:237], 0, s[4:5]
	v_permlane16_swap_b32_e32 v110, v106
	v_permlane16_swap_b32_e32 v111, v107
	v_permlane16_swap_b32_e32 v112, v108
	v_permlane16_swap_b32_e32 v113, v109
	v_permlane16_swap_b32_e32 v102, v94
	v_permlane16_swap_b32_e32 v103, v95
	v_permlane16_swap_b32_e32 v104, v96
	v_permlane16_swap_b32_e32 v105, v97
	s_mov_b64 s[4:5], 0x8000
	v_lshl_add_u64 v[232:233], v[232:233], 0, s[4:5]
	v_lshl_add_u64 v[234:235], v[234:235], 0, s[4:5]
	global_load_dwordx4 v[176:179], v[232:233], off nt
	global_load_dwordx4 v[180:183], v[232:233], off offset:256 nt
	global_load_dwordx4 v[184:187], v[234:235], off
	global_load_dwordx4 v[188:191], v[234:235], off offset:256
	s_waitcnt vmcnt(6)
; __device__ __forceinline__ float bflo(uint32_t v) { return __uint_as_float(v << 16); }
; __device__ __forceinline__ float bfhi(uint32_t v) { return __uint_as_float(v & 0xFFFF0000u); }
;   __device__ __forceinline__ void operator()(const acc8_t& acc, const pg8::Unit& u, int wr, int wc, int fr, int fq) const {
;     ...
; #pragma unroll
;     for (int ai = 0; ai < 2; ai++)
; #pragma unroll
;       for (int m = 0; m < 4; m++) {
;         const size_t token = EPI_TOKEN(u, ai, m);
; #pragma unroll
;         for (int bj = 0; bj < 2; bj++)
; #pragma unroll
;           for (int n = 0; n < 2; n++) {
;             const int f = EPI_COL(u, bj, n);
;             const uint2 gb = *(const uint2*)(GB + token * 1024 + f);
;             const uint2 mo = *(const uint2*)(M + token * 1024 + f);
;             uint2 o;
;             o.x = pack2(bflo(mo.x) + bflo(gb.x) * acc[ai][bj][m][n][0], bfhi(mo.x) + bfhi(gb.x) * acc[ai][bj][m][n][1]);
;             o.y = pack2(bflo(mo.y) + bflo(gb.y) * acc[ai][bj][m][n][2], bfhi(mo.y) + bfhi(gb.y) * acc[ai][bj][m][n][3]);
;             *(uint2*)(M + token * 1024 + f) = o;
	v_lshlrev_b32_e32 v208, 16, v192
	v_and_b32_e32 v209, 0xffff0000, v192
	v_lshlrev_b32_e32 v216, 16, v200
	v_and_b32_e32 v217, 0xffff0000, v200
	v_pk_fma_f32 v[110:111], v[110:111], v[208:209], v[216:217]
	v_lshlrev_b32_e32 v210, 16, v193
	v_and_b32_e32 v211, 0xffff0000, v193
	v_lshlrev_b32_e32 v218, 16, v201
	v_and_b32_e32 v219, 0xffff0000, v201
	v_pk_fma_f32 v[112:113], v[112:113], v[210:211], v[218:219]
	v_lshlrev_b32_e32 v212, 16, v194
	v_and_b32_e32 v213, 0xffff0000, v194
	v_lshlrev_b32_e32 v220, 16, v202
	v_and_b32_e32 v221, 0xffff0000, v202
	v_pk_fma_f32 v[106:107], v[106:107], v[212:213], v[220:221]
	v_lshlrev_b32_e32 v214, 16, v195
	v_and_b32_e32 v215, 0xffff0000, v195
	v_lshlrev_b32_e32 v222, 16, v203
	v_and_b32_e32 v223, 0xffff0000, v203
	v_pk_fma_f32 v[108:109], v[108:109], v[214:215], v[222:223]
	v_cvt_pk_bf16_f32 v224, v110, v111
	v_cvt_pk_bf16_f32 v225, v112, v113
	v_cvt_pk_bf16_f32 v226, v106, v107
	v_cvt_pk_bf16_f32 v227, v108, v109
	v_lshlrev_b32_e32 v208, 16, v196
	v_and_b32_e32 v209, 0xffff0000, v196
	v_lshlrev_b32_e32 v216, 16, v204
	v_and_b32_e32 v217, 0xffff0000, v204
	v_pk_fma_f32 v[102:103], v[102:103], v[208:209], v[216:217]
	v_lshlrev_b32_e32 v210, 16, v197
	v_and_b32_e32 v211, 0xffff0000, v197
	v_lshlrev_b32_e32 v218, 16, v205
	v_and_b32_e32 v219, 0xffff0000, v205
	v_pk_fma_f32 v[104:105], v[104:105], v[210:211], v[218:219]
	v_lshlrev_b32_e32 v212, 16, v198
	v_and_b32_e32 v213, 0xffff0000, v198
	v_lshlrev_b32_e32 v220, 16, v206
	v_and_b32_e32 v221, 0xffff0000, v206
	v_pk_fma_f32 v[94:95], v[94:95], v[212:213], v[220:221]
	v_lshlrev_b32_e32 v214, 16, v199
	v_and_b32_e32 v215, 0xffff0000, v199
	v_lshlrev_b32_e32 v222, 16, v207
	v_and_b32_e32 v223, 0xffff0000, v207
	v_pk_fma_f32 v[96:97], v[96:97], v[214:215], v[222:223]
	v_cvt_pk_bf16_f32 v228, v102, v103
	v_cvt_pk_bf16_f32 v229, v104, v105
	v_cvt_pk_bf16_f32 v230, v94, v95
	v_cvt_pk_bf16_f32 v231, v96, v97
	global_store_dwordx4 v[236:237], v[224:227], off
	global_store_dwordx4 v[236:237], v[228:231], off offset:256
	v_lshl_add_u64 v[236:237], v[236:237], 0, s[4:5]
	v_permlane16_swap_b32_e32 v98, v90
	v_permlane16_swap_b32_e32 v99, v91
	v_permlane16_swap_b32_e32 v100, v92
	v_permlane16_swap_b32_e32 v101, v93
	v_permlane16_swap_b32_e32 v78, v74
	v_permlane16_swap_b32_e32 v79, v75
	v_permlane16_swap_b32_e32 v80, v76
	v_permlane16_swap_b32_e32 v81, v77
	s_mov_b64 s[4:5], 0x8000
	v_lshl_add_u64 v[232:233], v[232:233], 0, s[4:5]
	v_lshl_add_u64 v[234:235], v[234:235], 0, s[4:5]
	global_load_dwordx4 v[192:195], v[232:233], off nt
	global_load_dwordx4 v[196:199], v[232:233], off offset:256 nt
	global_load_dwordx4 v[200:203], v[234:235], off
	global_load_dwordx4 v[204:207], v[234:235], off offset:256
	s_waitcnt vmcnt(6)
	v_lshlrev_b32_e32 v208, 16, v176
	v_and_b32_e32 v209, 0xffff0000, v176
	v_lshlrev_b32_e32 v216, 16, v184
	v_and_b32_e32 v217, 0xffff0000, v184
	v_pk_fma_f32 v[98:99], v[98:99], v[208:209], v[216:217]
	v_lshlrev_b32_e32 v210, 16, v177
	v_and_b32_e32 v211, 0xffff0000, v177
	v_lshlrev_b32_e32 v218, 16, v185
	v_and_b32_e32 v219, 0xffff0000, v185
	v_pk_fma_f32 v[100:101], v[100:101], v[210:211], v[218:219]
	v_lshlrev_b32_e32 v212, 16, v178
	v_and_b32_e32 v213, 0xffff0000, v178
	v_lshlrev_b32_e32 v220, 16, v186
	v_and_b32_e32 v221, 0xffff0000, v186
	v_pk_fma_f32 v[90:91], v[90:91], v[212:213], v[220:221]
	v_lshlrev_b32_e32 v214, 16, v179
	v_and_b32_e32 v215, 0xffff0000, v179
	v_lshlrev_b32_e32 v222, 16, v187
	v_and_b32_e32 v223, 0xffff0000, v187
	v_pk_fma_f32 v[92:93], v[92:93], v[214:215], v[222:223]
	v_cvt_pk_bf16_f32 v224, v98, v99
	v_cvt_pk_bf16_f32 v225, v100, v101
	v_cvt_pk_bf16_f32 v226, v90, v91
	v_cvt_pk_bf16_f32 v227, v92, v93
	v_lshlrev_b32_e32 v208, 16, v180
	v_and_b32_e32 v209, 0xffff0000, v180
	v_lshlrev_b32_e32 v216, 16, v188
	v_and_b32_e32 v217, 0xffff0000, v188
	v_pk_fma_f32 v[78:79], v[78:79], v[208:209], v[216:217]
	v_lshlrev_b32_e32 v210, 16, v181
	v_and_b32_e32 v211, 0xffff0000, v181
	v_lshlrev_b32_e32 v218, 16, v189
	v_and_b32_e32 v219, 0xffff0000, v189
	v_pk_fma_f32 v[80:81], v[80:81], v[210:211], v[218:219]
	v_lshlrev_b32_e32 v212, 16, v182
	v_and_b32_e32 v213, 0xffff0000, v182
	v_lshlrev_b32_e32 v220, 16, v190
	v_and_b32_e32 v221, 0xffff0000, v190
	v_pk_fma_f32 v[74:75], v[74:75], v[212:213], v[220:221]
	v_lshlrev_b32_e32 v214, 16, v183
	v_and_b32_e32 v215, 0xffff0000, v183
	v_lshlrev_b32_e32 v222, 16, v191
	v_and_b32_e32 v223, 0xffff0000, v191
	v_pk_fma_f32 v[76:77], v[76:77], v[214:215], v[222:223]
	v_cvt_pk_bf16_f32 v228, v78, v79
	v_cvt_pk_bf16_f32 v229, v80, v81
	v_cvt_pk_bf16_f32 v230, v74, v75
	v_cvt_pk_bf16_f32 v231, v76, v77
	global_store_dwordx4 v[236:237], v[224:227], off
	global_store_dwordx4 v[236:237], v[228:231], off offset:256
	v_lshl_add_u64 v[236:237], v[236:237], 0, s[4:5]
	v_permlane16_swap_b32_e32 v86, v82
	v_permlane16_swap_b32_e32 v87, v83
	v_permlane16_swap_b32_e32 v88, v84
	v_permlane16_swap_b32_e32 v89, v85
	v_permlane16_swap_b32_e32 v70, v66
	v_permlane16_swap_b32_e32 v71, v67
	v_permlane16_swap_b32_e32 v72, v68
	v_permlane16_swap_b32_e32 v73, v69
	s_mov_b64 s[4:5], 0x28000
	v_lshl_add_u64 v[232:233], v[232:233], 0, s[4:5]
	v_lshl_add_u64 v[234:235], v[234:235], 0, s[4:5]
	global_load_dwordx4 v[176:179], v[232:233], off nt
	global_load_dwordx4 v[180:183], v[232:233], off offset:256 nt
	global_load_dwordx4 v[184:187], v[234:235], off
	global_load_dwordx4 v[188:191], v[234:235], off offset:256
	s_waitcnt vmcnt(6)
; __device__ __forceinline__ float bflo(uint32_t v) { return __uint_as_float(v << 16); }
; __device__ __forceinline__ float bfhi(uint32_t v) { return __uint_as_float(v & 0xFFFF0000u); }
;   __device__ __forceinline__ void operator()(const acc8_t& acc, const pg8::Unit& u, int wr, int wc, int fr, int fq) const {
;     ...
; #pragma unroll
;     for (int ai = 0; ai < 2; ai++)
; #pragma unroll
;       for (int m = 0; m < 4; m++) {
;         const size_t token = EPI_TOKEN(u, ai, m);
; #pragma unroll
;         for (int bj = 0; bj < 2; bj++)
; #pragma unroll
;           for (int n = 0; n < 2; n++) {
;             const int f = EPI_COL(u, bj, n);
;             const uint2 gb = *(const uint2*)(GB + token * 1024 + f);
;             const uint2 mo = *(const uint2*)(M + token * 1024 + f);
;             uint2 o;
;             o.x = pack2(bflo(mo.x) + bflo(gb.x) * acc[ai][bj][m][n][0], bfhi(mo.x) + bfhi(gb.x) * acc[ai][bj][m][n][1]);
;             o.y = pack2(bflo(mo.y) + bflo(gb.y) * acc[ai][bj][m][n][2], bfhi(mo.y) + bfhi(gb.y) * acc[ai][bj][m][n][3]);
;             *(uint2*)(M + token * 1024 + f) = o;
	v_lshlrev_b32_e32 v208, 16, v192
	v_and_b32_e32 v209, 0xffff0000, v192
	v_lshlrev_b32_e32 v216, 16, v200
	v_and_b32_e32 v217, 0xffff0000, v200
	v_pk_fma_f32 v[86:87], v[86:87], v[208:209], v[216:217]
	v_lshlrev_b32_e32 v210, 16, v193
	v_and_b32_e32 v211, 0xffff0000, v193
	v_lshlrev_b32_e32 v218, 16, v201
	v_and_b32_e32 v219, 0xffff0000, v201
	v_pk_fma_f32 v[88:89], v[88:89], v[210:211], v[218:219]
	v_lshlrev_b32_e32 v212, 16, v194
	v_and_b32_e32 v213, 0xffff0000, v194
	v_lshlrev_b32_e32 v220, 16, v202
	v_and_b32_e32 v221, 0xffff0000, v202
	v_pk_fma_f32 v[82:83], v[82:83], v[212:213], v[220:221]
	v_lshlrev_b32_e32 v214, 16, v195
	v_and_b32_e32 v215, 0xffff0000, v195
	v_lshlrev_b32_e32 v222, 16, v203
	v_and_b32_e32 v223, 0xffff0000, v203
	v_pk_fma_f32 v[84:85], v[84:85], v[214:215], v[222:223]
	v_cvt_pk_bf16_f32 v224, v86, v87
	v_cvt_pk_bf16_f32 v225, v88, v89
	v_cvt_pk_bf16_f32 v226, v82, v83
	v_cvt_pk_bf16_f32 v227, v84, v85
	v_lshlrev_b32_e32 v208, 16, v196
	v_and_b32_e32 v209, 0xffff0000, v196
	v_lshlrev_b32_e32 v216, 16, v204
	v_and_b32_e32 v217, 0xffff0000, v204
	v_pk_fma_f32 v[70:71], v[70:71], v[208:209], v[216:217]
	v_lshlrev_b32_e32 v210, 16, v197
	v_and_b32_e32 v211, 0xffff0000, v197
	v_lshlrev_b32_e32 v218, 16, v205
	v_and_b32_e32 v219, 0xffff0000, v205
	v_pk_fma_f32 v[72:73], v[72:73], v[210:211], v[218:219]
	v_lshlrev_b32_e32 v212, 16, v198
	v_and_b32_e32 v213, 0xffff0000, v198
	v_lshlrev_b32_e32 v220, 16, v206
	v_and_b32_e32 v221, 0xffff0000, v206
	v_pk_fma_f32 v[66:67], v[66:67], v[212:213], v[220:221]
	v_lshlrev_b32_e32 v214, 16, v199
	v_and_b32_e32 v215, 0xffff0000, v199
	v_lshlrev_b32_e32 v222, 16, v207
	v_and_b32_e32 v223, 0xffff0000, v207
	v_pk_fma_f32 v[68:69], v[68:69], v[214:215], v[222:223]
	v_cvt_pk_bf16_f32 v228, v70, v71
	v_cvt_pk_bf16_f32 v229, v72, v73
	v_cvt_pk_bf16_f32 v230, v66, v67
	v_cvt_pk_bf16_f32 v231, v68, v69
	global_store_dwordx4 v[236:237], v[224:227], off
	global_store_dwordx4 v[236:237], v[228:231], off offset:256
	v_lshl_add_u64 v[236:237], v[236:237], 0, s[4:5]
	v_permlane16_swap_b32_e32 v62, v58
	v_permlane16_swap_b32_e32 v63, v59
	v_permlane16_swap_b32_e32 v64, v60
	v_permlane16_swap_b32_e32 v65, v61
	v_permlane16_swap_b32_e32 v54, v50
	v_permlane16_swap_b32_e32 v55, v51
	v_permlane16_swap_b32_e32 v56, v52
	v_permlane16_swap_b32_e32 v57, v53
	s_mov_b64 s[4:5], 0x8000
	v_lshl_add_u64 v[232:233], v[232:233], 0, s[4:5]
	v_lshl_add_u64 v[234:235], v[234:235], 0, s[4:5]
	global_load_dwordx4 v[192:195], v[232:233], off nt
	global_load_dwordx4 v[196:199], v[232:233], off offset:256 nt
	global_load_dwordx4 v[200:203], v[234:235], off
	global_load_dwordx4 v[204:207], v[234:235], off offset:256
	s_waitcnt vmcnt(6)
	v_lshlrev_b32_e32 v208, 16, v176
	v_and_b32_e32 v209, 0xffff0000, v176
	v_lshlrev_b32_e32 v216, 16, v184
	v_and_b32_e32 v217, 0xffff0000, v184
	v_pk_fma_f32 v[62:63], v[62:63], v[208:209], v[216:217]
	v_lshlrev_b32_e32 v210, 16, v177
	v_and_b32_e32 v211, 0xffff0000, v177
	v_lshlrev_b32_e32 v218, 16, v185
	v_and_b32_e32 v219, 0xffff0000, v185
	v_pk_fma_f32 v[64:65], v[64:65], v[210:211], v[218:219]
	v_lshlrev_b32_e32 v212, 16, v178
	v_and_b32_e32 v213, 0xffff0000, v178
	v_lshlrev_b32_e32 v220, 16, v186
	v_and_b32_e32 v221, 0xffff0000, v186
	v_pk_fma_f32 v[58:59], v[58:59], v[212:213], v[220:221]
	v_lshlrev_b32_e32 v214, 16, v179
	v_and_b32_e32 v215, 0xffff0000, v179
	v_lshlrev_b32_e32 v222, 16, v187
	v_and_b32_e32 v223, 0xffff0000, v187
	v_pk_fma_f32 v[60:61], v[60:61], v[214:215], v[222:223]
	v_cvt_pk_bf16_f32 v224, v62, v63
	v_cvt_pk_bf16_f32 v225, v64, v65
	v_cvt_pk_bf16_f32 v226, v58, v59
	v_cvt_pk_bf16_f32 v227, v60, v61
	v_lshlrev_b32_e32 v208, 16, v180
	v_and_b32_e32 v209, 0xffff0000, v180
	v_lshlrev_b32_e32 v216, 16, v188
	v_and_b32_e32 v217, 0xffff0000, v188
	v_pk_fma_f32 v[54:55], v[54:55], v[208:209], v[216:217]
	v_lshlrev_b32_e32 v210, 16, v181
	v_and_b32_e32 v211, 0xffff0000, v181
	v_lshlrev_b32_e32 v218, 16, v189
	v_and_b32_e32 v219, 0xffff0000, v189
	v_pk_fma_f32 v[56:57], v[56:57], v[210:211], v[218:219]
	v_lshlrev_b32_e32 v212, 16, v182
	v_and_b32_e32 v213, 0xffff0000, v182
	v_lshlrev_b32_e32 v220, 16, v190
	v_and_b32_e32 v221, 0xffff0000, v190
	v_pk_fma_f32 v[50:51], v[50:51], v[212:213], v[220:221]
	v_lshlrev_b32_e32 v214, 16, v183
	v_and_b32_e32 v215, 0xffff0000, v183
	v_lshlrev_b32_e32 v222, 16, v191
	v_and_b32_e32 v223, 0xffff0000, v191
	v_pk_fma_f32 v[52:53], v[52:53], v[214:215], v[222:223]
	v_cvt_pk_bf16_f32 v228, v54, v55
	v_cvt_pk_bf16_f32 v229, v56, v57
	v_cvt_pk_bf16_f32 v230, v50, v51
	v_cvt_pk_bf16_f32 v231, v52, v53
	global_store_dwordx4 v[236:237], v[224:227], off
	global_store_dwordx4 v[236:237], v[228:231], off offset:256
	v_lshl_add_u64 v[236:237], v[236:237], 0, s[4:5]
	v_permlane16_swap_b32_e32 v46, v42
	v_permlane16_swap_b32_e32 v47, v43
	v_permlane16_swap_b32_e32 v48, v44
	v_permlane16_swap_b32_e32 v49, v45
	v_permlane16_swap_b32_e32 v38, v34
	v_permlane16_swap_b32_e32 v39, v35
	v_permlane16_swap_b32_e32 v40, v36
	v_permlane16_swap_b32_e32 v41, v37
	s_mov_b64 s[4:5], 0x8000
	v_lshl_add_u64 v[232:233], v[232:233], 0, s[4:5]
	v_lshl_add_u64 v[234:235], v[234:235], 0, s[4:5]
	global_load_dwordx4 v[176:179], v[232:233], off nt
	global_load_dwordx4 v[180:183], v[232:233], off offset:256 nt
	global_load_dwordx4 v[184:187], v[234:235], off
	global_load_dwordx4 v[188:191], v[234:235], off offset:256
	s_waitcnt vmcnt(6)
; __device__ __forceinline__ float bflo(uint32_t v) { return __uint_as_float(v << 16); }
; __device__ __forceinline__ float bfhi(uint32_t v) { return __uint_as_float(v & 0xFFFF0000u); }
;   __device__ __forceinline__ void operator()(const acc8_t& acc, const pg8::Unit& u, int wr, int wc, int fr, int fq) const {
;     ...
; #pragma unroll
;     for (int ai = 0; ai < 2; ai++)
; #pragma unroll
;       for (int m = 0; m < 4; m++) {
;         const size_t token = EPI_TOKEN(u, ai, m);
; #pragma unroll
;         for (int bj = 0; bj < 2; bj++)
; #pragma unroll
;           for (int n = 0; n < 2; n++) {
;             const int f = EPI_COL(u, bj, n);
;             const uint2 gb = *(const uint2*)(GB + token * 1024 + f);
;             const uint2 mo = *(const uint2*)(M + token * 1024 + f);
;             uint2 o;
;             o.x = pack2(bflo(mo.x) + bflo(gb.x) * acc[ai][bj][m][n][0], bfhi(mo.x) + bfhi(gb.x) * acc[ai][bj][m][n][1]);
;             o.y = pack2(bflo(mo.y) + bflo(gb.y) * acc[ai][bj][m][n][2], bfhi(mo.y) + bfhi(gb.y) * acc[ai][bj][m][n][3]);
;             *(uint2*)(M + token * 1024 + f) = o;
	v_lshlrev_b32_e32 v208, 16, v192
	v_and_b32_e32 v209, 0xffff0000, v192
	v_lshlrev_b32_e32 v216, 16, v200
	v_and_b32_e32 v217, 0xffff0000, v200
	v_pk_fma_f32 v[46:47], v[46:47], v[208:209], v[216:217]
	v_lshlrev_b32_e32 v210, 16, v193
	v_and_b32_e32 v211, 0xffff0000, v193
	v_lshlrev_b32_e32 v218, 16, v201
	v_and_b32_e32 v219, 0xffff0000, v201
	v_pk_fma_f32 v[48:49], v[48:49], v[210:211], v[218:219]
	v_lshlrev_b32_e32 v212, 16, v194
	v_and_b32_e32 v213, 0xffff0000, v194
	v_lshlrev_b32_e32 v220, 16, v202
	v_and_b32_e32 v221, 0xffff0000, v202
	v_pk_fma_f32 v[42:43], v[42:43], v[212:213], v[220:221]
	v_lshlrev_b32_e32 v214, 16, v195
	v_and_b32_e32 v215, 0xffff0000, v195
	v_lshlrev_b32_e32 v222, 16, v203
	v_and_b32_e32 v223, 0xffff0000, v203
	v_pk_fma_f32 v[44:45], v[44:45], v[214:215], v[222:223]
	v_cvt_pk_bf16_f32 v224, v46, v47
	v_cvt_pk_bf16_f32 v225, v48, v49
	v_cvt_pk_bf16_f32 v226, v42, v43
	v_cvt_pk_bf16_f32 v227, v44, v45
	v_lshlrev_b32_e32 v208, 16, v196
	v_and_b32_e32 v209, 0xffff0000, v196
	v_lshlrev_b32_e32 v216, 16, v204
	v_and_b32_e32 v217, 0xffff0000, v204
	v_pk_fma_f32 v[38:39], v[38:39], v[208:209], v[216:217]
	v_lshlrev_b32_e32 v210, 16, v197
	v_and_b32_e32 v211, 0xffff0000, v197
	v_lshlrev_b32_e32 v218, 16, v205
	v_and_b32_e32 v219, 0xffff0000, v205
	v_pk_fma_f32 v[40:41], v[40:41], v[210:211], v[218:219]
	v_lshlrev_b32_e32 v212, 16, v198
	v_and_b32_e32 v213, 0xffff0000, v198
	v_lshlrev_b32_e32 v220, 16, v206
	v_and_b32_e32 v221, 0xffff0000, v206
	v_pk_fma_f32 v[34:35], v[34:35], v[212:213], v[220:221]
	v_lshlrev_b32_e32 v214, 16, v199
	v_and_b32_e32 v215, 0xffff0000, v199
	v_lshlrev_b32_e32 v222, 16, v207
	v_and_b32_e32 v223, 0xffff0000, v207
	v_pk_fma_f32 v[36:37], v[36:37], v[214:215], v[222:223]
	v_cvt_pk_bf16_f32 v228, v38, v39
	v_cvt_pk_bf16_f32 v229, v40, v41
	v_cvt_pk_bf16_f32 v230, v34, v35
	v_cvt_pk_bf16_f32 v231, v36, v37
	global_store_dwordx4 v[236:237], v[224:227], off
	global_store_dwordx4 v[236:237], v[228:231], off offset:256
	v_lshl_add_u64 v[236:237], v[236:237], 0, s[4:5]
	v_permlane16_swap_b32_e32 v30, v26
	v_permlane16_swap_b32_e32 v31, v27
	v_permlane16_swap_b32_e32 v32, v28
	v_permlane16_swap_b32_e32 v33, v29
	v_permlane16_swap_b32_e32 v22, v18
	v_permlane16_swap_b32_e32 v23, v19
	v_permlane16_swap_b32_e32 v24, v20
	v_permlane16_swap_b32_e32 v25, v21
	s_mov_b64 s[4:5], 0x8000
	v_lshl_add_u64 v[232:233], v[232:233], 0, s[4:5]
	v_lshl_add_u64 v[234:235], v[234:235], 0, s[4:5]
	global_load_dwordx4 v[192:195], v[232:233], off nt
	global_load_dwordx4 v[196:199], v[232:233], off offset:256 nt
	global_load_dwordx4 v[200:203], v[234:235], off
	global_load_dwordx4 v[204:207], v[234:235], off offset:256
	s_waitcnt vmcnt(6)
; __device__ __forceinline__ float bflo(uint32_t v) { return __uint_as_float(v << 16); }
; __device__ __forceinline__ float bfhi(uint32_t v) { return __uint_as_float(v & 0xFFFF0000u); }
; #define PG8_WAIT_V(n) asm volatile("s_waitcnt vmcnt(" #n ")" ::: "memory")
; #define PG8_BAR __builtin_amdgcn_s_barrier()
; template <class Epi, class Sched>
; __device__ __forceinline__ void gemm_phase(PG8_LAS unsigned char* lds, const Gemm g, const Sched& S, const Epi& E) {
;     ...
;         E(acc, cur, wr, wc, fr, fq);
;         if (!has_next) break;
; #pragma unroll
;         for (int a = 0; a < 2; ++a)
; #pragma unroll
;             for (int b = 0; b < 2; ++b)
; #pragma unroll
;                 for (int m = 0; m < 4; ++m)
; #pragma unroll
;                     for (int n = 0; n < 2; ++n) acc[a][b][m][n] = (f32x4){0.f, 0.f, 0.f, 0.f};
;         cur = nxt; cA = nA; cB = nB; ++ui;
;     }
;     PG8_WAIT_V(0);
;     if (wr == 0) PG8_BAR;
;     PG8_BAR;
;   __device__ __forceinline__ void operator()(const acc8_t& acc, const pg8::Unit& u, int wr, int wc, int fr, int fq) const {
;     ...
; #pragma unroll
;     for (int ai = 0; ai < 2; ai++)
; #pragma unroll
;       for (int m = 0; m < 4; m++) {
;         const size_t token = EPI_TOKEN(u, ai, m);
; #pragma unroll
;         for (int bj = 0; bj < 2; bj++)
; #pragma unroll
;           for (int n = 0; n < 2; n++) {
;             const int f = EPI_COL(u, bj, n);
;             const uint2 gb = *(const uint2*)(GB + token * 1024 + f);
;             const uint2 mo = *(const uint2*)(M + token * 1024 + f);
;             uint2 o;
;             o.x = pack2(bflo(mo.x) + bflo(gb.x) * acc[ai][bj][m][n][0], bfhi(mo.x) + bfhi(gb.x) * acc[ai][bj][m][n][1]);
;             o.y = pack2(bflo(mo.y) + bflo(gb.y) * acc[ai][bj][m][n][2], bfhi(mo.y) + bfhi(gb.y) * acc[ai][bj][m][n][3]);
;             *(uint2*)(M + token * 1024 + f) = o;
	v_lshlrev_b32_e32 v208, 16, v176
	v_and_b32_e32 v209, 0xffff0000, v176
	v_lshlrev_b32_e32 v216, 16, v184
	v_and_b32_e32 v217, 0xffff0000, v184
	v_pk_fma_f32 v[30:31], v[30:31], v[208:209], v[216:217]
	v_lshlrev_b32_e32 v210, 16, v177
	v_and_b32_e32 v211, 0xffff0000, v177
	v_lshlrev_b32_e32 v218, 16, v185
	v_and_b32_e32 v219, 0xffff0000, v185
	v_pk_fma_f32 v[32:33], v[32:33], v[210:211], v[218:219]
	v_lshlrev_b32_e32 v212, 16, v178
	v_and_b32_e32 v213, 0xffff0000, v178
	v_lshlrev_b32_e32 v220, 16, v186
	v_and_b32_e32 v221, 0xffff0000, v186
	v_pk_fma_f32 v[26:27], v[26:27], v[212:213], v[220:221]
	v_lshlrev_b32_e32 v214, 16, v179
	v_and_b32_e32 v215, 0xffff0000, v179
	v_lshlrev_b32_e32 v222, 16, v187
	v_and_b32_e32 v223, 0xffff0000, v187
	v_pk_fma_f32 v[28:29], v[28:29], v[214:215], v[222:223]
	v_cvt_pk_bf16_f32 v224, v30, v31
	v_cvt_pk_bf16_f32 v225, v32, v33
	v_cvt_pk_bf16_f32 v226, v26, v27
	v_cvt_pk_bf16_f32 v227, v28, v29
	v_lshlrev_b32_e32 v208, 16, v180
	v_and_b32_e32 v209, 0xffff0000, v180
	v_lshlrev_b32_e32 v216, 16, v188
	v_and_b32_e32 v217, 0xffff0000, v188
	v_pk_fma_f32 v[22:23], v[22:23], v[208:209], v[216:217]
	v_lshlrev_b32_e32 v210, 16, v181
	v_and_b32_e32 v211, 0xffff0000, v181
	v_lshlrev_b32_e32 v218, 16, v189
	v_and_b32_e32 v219, 0xffff0000, v189
	v_pk_fma_f32 v[24:25], v[24:25], v[210:211], v[218:219]
	v_lshlrev_b32_e32 v212, 16, v182
	v_and_b32_e32 v213, 0xffff0000, v182
	v_lshlrev_b32_e32 v220, 16, v190
	v_and_b32_e32 v221, 0xffff0000, v190
	v_pk_fma_f32 v[18:19], v[18:19], v[212:213], v[220:221]
	v_lshlrev_b32_e32 v214, 16, v183
	v_and_b32_e32 v215, 0xffff0000, v183
	v_lshlrev_b32_e32 v222, 16, v191
	v_and_b32_e32 v223, 0xffff0000, v191
	v_pk_fma_f32 v[20:21], v[20:21], v[214:215], v[222:223]
	v_cvt_pk_bf16_f32 v228, v22, v23
	v_cvt_pk_bf16_f32 v229, v24, v25
	v_cvt_pk_bf16_f32 v230, v18, v19
	v_cvt_pk_bf16_f32 v231, v20, v21
	global_store_dwordx4 v[236:237], v[224:227], off
	global_store_dwordx4 v[236:237], v[228:231], off offset:256
	v_lshl_add_u64 v[236:237], v[236:237], 0, s[4:5]
	v_permlane16_swap_b32_e32 v14, v10
	v_permlane16_swap_b32_e32 v15, v11
	v_permlane16_swap_b32_e32 v16, v12
	v_permlane16_swap_b32_e32 v17, v13
	v_permlane16_swap_b32_e32 v6, v2
	v_permlane16_swap_b32_e32 v7, v3
	v_permlane16_swap_b32_e32 v8, v4
	v_permlane16_swap_b32_e32 v9, v5
	s_waitcnt vmcnt(2)
	v_lshlrev_b32_e32 v208, 16, v192
	v_and_b32_e32 v209, 0xffff0000, v192
	v_lshlrev_b32_e32 v216, 16, v200
	v_and_b32_e32 v217, 0xffff0000, v200
	v_pk_fma_f32 v[14:15], v[14:15], v[208:209], v[216:217]
	v_lshlrev_b32_e32 v210, 16, v193
	v_and_b32_e32 v211, 0xffff0000, v193
	v_lshlrev_b32_e32 v218, 16, v201
	v_and_b32_e32 v219, 0xffff0000, v201
	v_pk_fma_f32 v[16:17], v[16:17], v[210:211], v[218:219]
	v_lshlrev_b32_e32 v212, 16, v194
	v_and_b32_e32 v213, 0xffff0000, v194
	v_lshlrev_b32_e32 v220, 16, v202
	v_and_b32_e32 v221, 0xffff0000, v202
	v_pk_fma_f32 v[10:11], v[10:11], v[212:213], v[220:221]
	v_lshlrev_b32_e32 v214, 16, v195
	v_and_b32_e32 v215, 0xffff0000, v195
	v_lshlrev_b32_e32 v222, 16, v203
	v_and_b32_e32 v223, 0xffff0000, v203
	v_pk_fma_f32 v[12:13], v[12:13], v[214:215], v[222:223]
	v_cvt_pk_bf16_f32 v224, v14, v15
	v_cvt_pk_bf16_f32 v225, v16, v17
	v_cvt_pk_bf16_f32 v226, v10, v11
	v_cvt_pk_bf16_f32 v227, v12, v13
	v_lshlrev_b32_e32 v208, 16, v196
	v_and_b32_e32 v209, 0xffff0000, v196
	v_lshlrev_b32_e32 v216, 16, v204
	v_and_b32_e32 v217, 0xffff0000, v204
	v_pk_fma_f32 v[6:7], v[6:7], v[208:209], v[216:217]
	v_lshlrev_b32_e32 v210, 16, v197
	v_and_b32_e32 v211, 0xffff0000, v197
	v_lshlrev_b32_e32 v218, 16, v205
	v_and_b32_e32 v219, 0xffff0000, v205
	v_pk_fma_f32 v[8:9], v[8:9], v[210:211], v[218:219]
	v_lshlrev_b32_e32 v212, 16, v198
	v_and_b32_e32 v213, 0xffff0000, v198
	v_lshlrev_b32_e32 v220, 16, v206
	v_and_b32_e32 v221, 0xffff0000, v206
	v_pk_fma_f32 v[2:3], v[2:3], v[212:213], v[220:221]
	v_lshlrev_b32_e32 v214, 16, v199
	v_and_b32_e32 v215, 0xffff0000, v199
	v_lshlrev_b32_e32 v222, 16, v207
	v_and_b32_e32 v223, 0xffff0000, v207
	v_pk_fma_f32 v[4:5], v[4:5], v[214:215], v[222:223]
	v_cvt_pk_bf16_f32 v228, v6, v7
	v_cvt_pk_bf16_f32 v229, v8, v9
	v_cvt_pk_bf16_f32 v230, v2, v3
	v_cvt_pk_bf16_f32 v231, v4, v5
	global_store_dwordx4 v[236:237], v[224:227], off
	global_store_dwordx4 v[236:237], v[228:231], off offset:256
	s_and_b64 vcc, exec, s[16:17]
	s_cbranch_vccz .LBB0_707
	s_waitcnt vmcnt(0)
	s_cmpk_gt_u32 s33, 0xff
	s_cbranch_scc1 .LBB0_717
	s_barrier

; #define PG8_STAGE(bufoff, gbase, voff) do { _Pragma("unroll") for (int _i = 0; _i < 2; ++_i) \
;         __builtin_amdgcn_global_load_lds((const unsigned*)((const char*)(gbase) + (voff)[_i]), (PG8_LAS unsigned*)(lds + (bufoff) + ldsw + _i * 8192), 16, 0, 0); } while (0)
; #define PG8_LDA(dst, b, h) do { _Pragma("unroll") for (int m = 0; m < 4; ++m) _Pragma("unroll") for (int k = 0; k < 2; ++k) dst[m][k] = *(const PG8_LAS bf16x8*)(lds + PG8_SA(b, h) + aoff + m * 2048 + k * 1024); } while (0)
; #define PG8_LDB(dst, b, h) do { _Pragma("unroll") for (int n = 0; n < 2; ++n) _Pragma("unroll") for (int k = 0; k < 2; ++k) dst[n][k] = *(const PG8_LAS bf16x8*)(lds + PG8_SB(b, h) + boff + n * 2048 + k * 1024); } while (0)
; #define PG8_MMA(ai, bj, At, Bt) do { __builtin_amdgcn_s_setprio(1); _Pragma("unroll") for (int m = 0; m < 4; ++m) _Pragma("unroll") for (int n = 0; n < 2; ++n) _Pragma("unroll") for (int k = 0; k < 2; ++k) \
;         acc[ai][bj][m][n] = __builtin_amdgcn_mfma_f32_16x16x32_bf16(Bt[n][k], At[m][k], acc[ai][bj][m][n], 0, 0, 0); __builtin_amdgcn_s_setprio(0); } while (0)
; #define PG8_WAIT_V(n) asm volatile("s_waitcnt vmcnt(" #n ")" ::: "memory")
; #define PG8_WAIT_L(n) asm volatile("s_waitcnt lgkmcnt(" #n ")" ::: "memory")
; #define PG8_BAR __builtin_amdgcn_s_barrier()
; #define PG8_SCHED __builtin_amdgcn_sched_barrier(0)
; template <class Epi, class Sched>
; __device__ __forceinline__ void gemm_phase(PG8_LAS unsigned char* lds, const Gemm g, const Sched& S, const Epi& E) {
;     ...
;             PG8_LDB(B0, 0, 0); PG8_SCHED; PG8_LDA(At, 0, 0); PG8_STAGE(PG8_SA(1, 1), a1 + hstep, voffA);
;             PG8_WAIT_L(8); PG8_BAR; PG8_WAIT_L(0); PG8_MMA(0, 0, At, B0); PG8_BAR; PG8_SCHED;
;             PG8_LDB(B1, 0, 1); PG8_STAGE(PG8_SB(0, 0), b2, voffB);
;             PG8_BAR; PG8_WAIT_L(0); PG8_MMA(0, 1, At, B1); PG8_BAR;
;             PG8_LDA(At, 0, 1); PG8_STAGE(PG8_SA(0, 0), a2, voffA);
;             PG8_BAR; PG8_WAIT_L(0); PG8_MMA(1, 0, At, B0); PG8_BAR; PG8_SCHED;
;             PG8_STAGE(PG8_SB(0, 1), b2 + hstep, voffB);
;             PG8_WAIT_V(6); PG8_BAR; PG8_MMA(1, 1, At, B1); PG8_BAR;
;             PG8_LDB(B0, 1, 0); PG8_SCHED; PG8_LDA(At, 1, 0); PG8_STAGE(PG8_SA(0, 1), a2 + hstep, voffA);
;             PG8_WAIT_L(8); PG8_BAR; PG8_WAIT_L(0); PG8_MMA(0, 0, At, B0); PG8_BAR; PG8_SCHED;
.LBB0_828:
	ds_read_b128 v[138:141], v147
	ds_read_b128 v[164:167], v148
	ds_read_b128 v[168:171], v149
	ds_read_b128 v[172:175], v150
	s_add_u32 s24, s22, 0xfff00080
	s_addc_u32 s25, s23, -1
	s_cmp_eq_u32 s54, 60
	s_cselect_b32 s27, s11, s25
	s_cselect_b32 s26, s50, s24
	s_cselect_b32 s25, s9, s53
	s_cselect_b32 s24, s51, s52
	s_mov_b32 m0, s48
	v_lshl_add_u64 v[208:209], s[22:23], 0, v[134:135]
	ds_read_b128 v[176:179], v145
	ds_read_b128 v[180:183], v145 offset:1024
	ds_read_b128 v[184:187], v145 offset:2048
	ds_read_b128 v[188:191], v145 offset:3072
	ds_read_b128 v[192:195], v145 offset:4096
	ds_read_b128 v[196:199], v145 offset:5120
	ds_read_b128 v[200:203], v145 offset:6144
	ds_read_b128 v[204:207], v145 offset:7168
	global_load_lds_dwordx4 v[208:209], off
	v_lshl_add_u64 v[208:209], s[22:23], 0, v[136:137]
	s_mov_b32 m0, s49
	s_nop 0
	global_load_lds_dwordx4 v[208:209], off
	s_waitcnt lgkmcnt(8)
	s_barrier
	s_waitcnt lgkmcnt(0)
	s_setprio 1
	s_waitcnt lgkmcnt(0)
	v_mfma_f32_16x16x32_bf16 v[126:129], v[138:141], v[176:179], v[126:129]
	v_mfma_f32_16x16x32_bf16 v[122:125], v[168:171], v[176:179], v[122:125]
	v_mfma_f32_16x16x32_bf16 v[114:117], v[138:141], v[184:187], v[114:117]
	v_mfma_f32_16x16x32_bf16 v[106:109], v[168:171], v[184:187], v[106:109]
	v_mfma_f32_16x16x32_bf16 v[94:97], v[138:141], v[192:195], v[94:97]
	v_mfma_f32_16x16x32_bf16 v[90:93], v[168:171], v[192:195], v[90:93]
	v_mfma_f32_16x16x32_bf16 v[78:81], v[138:141], v[200:203], v[78:81]
	v_mfma_f32_16x16x32_bf16 v[74:77], v[168:171], v[200:203], v[74:77]
	v_mfma_f32_16x16x32_bf16 v[126:129], v[164:167], v[180:183], v[126:129]
	v_mfma_f32_16x16x32_bf16 v[122:125], v[172:175], v[180:183], v[122:125]
	v_mfma_f32_16x16x32_bf16 v[114:117], v[164:167], v[188:191], v[114:117]
	v_mfma_f32_16x16x32_bf16 v[106:109], v[172:175], v[188:191], v[106:109]
	v_mfma_f32_16x16x32_bf16 v[94:97], v[164:167], v[196:199], v[94:97]
	v_mfma_f32_16x16x32_bf16 v[90:93], v[172:175], v[196:199], v[90:93]
	v_mfma_f32_16x16x32_bf16 v[78:81], v[164:167], v[204:207], v[78:81]
	v_mfma_f32_16x16x32_bf16 v[74:77], v[172:175], v[204:207], v[74:77]
	s_setprio 0
	s_barrier
	s_mov_b32 m0, s19
	v_lshl_add_u64 v[224:225], s[24:25], 0, v[132:133]
	ds_read_b128 v[208:211], v151
	ds_read_b128 v[212:215], v152
	ds_read_b128 v[216:219], v153
	ds_read_b128 v[220:223], v154
	global_load_lds_dwordx4 v[224:225], off
	v_lshl_add_u64 v[226:227], s[24:25], 0, v[130:131]
	s_mov_b32 m0, s21
	s_nop 0
	global_load_lds_dwordx4 v[226:227], off
	s_barrier
	s_waitcnt lgkmcnt(0)
	s_setprio 1
	s_waitcnt lgkmcnt(0)
	v_mfma_f32_16x16x32_bf16 v[118:121], v[208:211], v[176:179], v[118:121]
	v_mfma_f32_16x16x32_bf16 v[110:113], v[216:219], v[176:179], v[110:113]
	v_mfma_f32_16x16x32_bf16 v[102:105], v[208:211], v[184:187], v[102:105]
	v_mfma_f32_16x16x32_bf16 v[98:101], v[216:219], v[184:187], v[98:101]
	v_mfma_f32_16x16x32_bf16 v[86:89], v[208:211], v[192:195], v[86:89]
	v_mfma_f32_16x16x32_bf16 v[82:85], v[216:219], v[192:195], v[82:85]
	v_mfma_f32_16x16x32_bf16 v[70:73], v[208:211], v[200:203], v[70:73]
	v_mfma_f32_16x16x32_bf16 v[66:69], v[216:219], v[200:203], v[66:69]
	v_mfma_f32_16x16x32_bf16 v[118:121], v[212:215], v[180:183], v[118:121]
	v_mfma_f32_16x16x32_bf16 v[110:113], v[220:223], v[180:183], v[110:113]
	v_mfma_f32_16x16x32_bf16 v[102:105], v[212:215], v[188:191], v[102:105]
	v_mfma_f32_16x16x32_bf16 v[98:101], v[220:223], v[188:191], v[98:101]
	v_mfma_f32_16x16x32_bf16 v[86:89], v[212:215], v[196:199], v[86:89]
	v_mfma_f32_16x16x32_bf16 v[82:85], v[220:223], v[196:199], v[82:85]
	v_mfma_f32_16x16x32_bf16 v[70:73], v[212:215], v[204:207], v[70:73]
	v_mfma_f32_16x16x32_bf16 v[66:69], v[220:223], v[204:207], v[66:69]
	s_setprio 0
	s_mov_b32 m0, s35
	v_lshl_add_u64 v[228:229], s[26:27], 0, v[132:133]
	s_barrier
	ds_read_b128 v[176:179], v145 offset:16384
	ds_read_b128 v[180:183], v145 offset:17408
	ds_read_b128 v[184:187], v145 offset:18432
	ds_read_b128 v[188:191], v145 offset:19456
	ds_read_b128 v[192:195], v145 offset:20480
	ds_read_b128 v[196:199], v145 offset:21504
	ds_read_b128 v[200:203], v145 offset:22528
	ds_read_b128 v[204:207], v145 offset:23552
	global_load_lds_dwordx4 v[228:229], off
	v_lshl_add_u64 v[230:231], s[26:27], 0, v[130:131]
	s_mov_b32 m0, s36
	s_nop 0
	global_load_lds_dwordx4 v[230:231], off
	s_barrier
	s_waitcnt lgkmcnt(0)
	s_setprio 1
	s_waitcnt lgkmcnt(0)
	v_mfma_f32_16x16x32_bf16 v[62:65], v[138:141], v[176:179], v[62:65]
	v_mfma_f32_16x16x32_bf16 v[58:61], v[168:171], v[176:179], v[58:61]
	v_mfma_f32_16x16x32_bf16 v[46:49], v[138:141], v[184:187], v[46:49]
	v_mfma_f32_16x16x32_bf16 v[42:45], v[168:171], v[184:187], v[42:45]
	v_mfma_f32_16x16x32_bf16 v[30:33], v[138:141], v[192:195], v[30:33]
	v_mfma_f32_16x16x32_bf16 v[26:29], v[168:171], v[192:195], v[26:29]
	v_mfma_f32_16x16x32_bf16 v[14:17], v[138:141], v[200:203], v[14:17]
	v_mfma_f32_16x16x32_bf16 v[10:13], v[168:171], v[200:203], v[10:13]
	v_mfma_f32_16x16x32_bf16 v[62:65], v[164:167], v[180:183], v[62:65]
	v_mfma_f32_16x16x32_bf16 v[58:61], v[172:175], v[180:183], v[58:61]
	v_mfma_f32_16x16x32_bf16 v[46:49], v[164:167], v[188:191], v[46:49]
	v_mfma_f32_16x16x32_bf16 v[42:45], v[172:175], v[188:191], v[42:45]
	v_mfma_f32_16x16x32_bf16 v[30:33], v[164:167], v[196:199], v[30:33]
	v_mfma_f32_16x16x32_bf16 v[26:29], v[172:175], v[196:199], v[26:29]
	v_mfma_f32_16x16x32_bf16 v[14:17], v[164:167], v[204:207], v[14:17]
	v_mfma_f32_16x16x32_bf16 v[10:13], v[172:175], v[204:207], v[10:13]
	s_setprio 0
	s_barrier
; #define PG8_STAGE(bufoff, gbase, voff) do { _Pragma("unroll") for (int _i = 0; _i < 2; ++_i) \
;         __builtin_amdgcn_global_load_lds((const unsigned*)((const char*)(gbase) + (voff)[_i]), (PG8_LAS unsigned*)(lds + (bufoff) + ldsw + _i * 8192), 16, 0, 0); } while (0)
; #define PG8_LDA(dst, b, h) do { _Pragma("unroll") for (int m = 0; m < 4; ++m) _Pragma("unroll") for (int k = 0; k < 2; ++k) dst[m][k] = *(const PG8_LAS bf16x8*)(lds + PG8_SA(b, h) + aoff + m * 2048 + k * 1024); } while (0)
; #define PG8_LDB(dst, b, h) do { _Pragma("unroll") for (int n = 0; n < 2; ++n) _Pragma("unroll") for (int k = 0; k < 2; ++k) dst[n][k] = *(const PG8_LAS bf16x8*)(lds + PG8_SB(b, h) + boff + n * 2048 + k * 1024); } while (0)
; #define PG8_MMA(ai, bj, At, Bt) do { __builtin_amdgcn_s_setprio(1); _Pragma("unroll") for (int m = 0; m < 4; ++m) _Pragma("unroll") for (int n = 0; n < 2; ++n) _Pragma("unroll") for (int k = 0; k < 2; ++k) \
;         acc[ai][bj][m][n] = __builtin_amdgcn_mfma_f32_16x16x32_bf16(Bt[n][k], At[m][k], acc[ai][bj][m][n], 0, 0, 0); __builtin_amdgcn_s_setprio(0); } while (0)
; #define PG8_WAIT_V(n) asm volatile("s_waitcnt vmcnt(" #n ")" ::: "memory")
; #define PG8_WAIT_L(n) asm volatile("s_waitcnt lgkmcnt(" #n ")" ::: "memory")
; #define PG8_BAR __builtin_amdgcn_s_barrier()
; #define PG8_SCHED __builtin_amdgcn_sched_barrier(0)
; template <class Epi, class Sched>
; __device__ __forceinline__ void gemm_phase(PG8_LAS unsigned char* lds, const Gemm g, const Sched& S, const Epi& E) {
;     ...
;             PG8_STAGE(PG8_SB(0, 1), b2 + hstep, voffB);
;             PG8_WAIT_V(6); PG8_BAR; PG8_MMA(1, 1, At, B1); PG8_BAR;
;             PG8_LDB(B0, 1, 0); PG8_SCHED; PG8_LDA(At, 1, 0); PG8_STAGE(PG8_SA(0, 1), a2 + hstep, voffA);
;             PG8_WAIT_L(8); PG8_BAR; PG8_WAIT_L(0); PG8_MMA(0, 0, At, B0); PG8_BAR; PG8_SCHED;
;             PG8_LDB(B1, 1, 1); PG8_STAGE(PG8_SB(1, 0), b3, voffB);
;             PG8_BAR; PG8_WAIT_L(0); PG8_MMA(0, 1, At, B1); PG8_BAR;
;             PG8_LDA(At, 1, 1); PG8_STAGE(PG8_SA(1, 0), a3, voffA);
;             PG8_BAR; PG8_WAIT_L(0); PG8_MMA(1, 0, At, B0); PG8_BAR; PG8_SCHED;
	s_add_u32 s56, s24, 0x100000
	s_addc_u32 s57, s25, 0
	s_mov_b32 m0, s37
	v_lshl_add_u64 v[138:139], s[56:57], 0, v[132:133]
	global_load_lds_dwordx4 v[138:139], off
	v_lshl_add_u64 v[138:139], s[56:57], 0, v[130:131]
	s_mov_b32 m0, s38
	s_nop 0
	global_load_lds_dwordx4 v[138:139], off
	s_waitcnt vmcnt(6)
	s_barrier
	s_setprio 1
	v_mfma_f32_16x16x32_bf16 v[54:57], v[208:211], v[176:179], v[54:57]
	v_mfma_f32_16x16x32_bf16 v[50:53], v[216:219], v[176:179], v[50:53]
	v_mfma_f32_16x16x32_bf16 v[38:41], v[208:211], v[184:187], v[38:41]
	v_mfma_f32_16x16x32_bf16 v[34:37], v[216:219], v[184:187], v[34:37]
	v_mfma_f32_16x16x32_bf16 v[22:25], v[208:211], v[192:195], v[22:25]
	v_mfma_f32_16x16x32_bf16 v[18:21], v[216:219], v[192:195], v[18:21]
	v_mfma_f32_16x16x32_bf16 v[6:9], v[208:211], v[200:203], v[6:9]
	v_mfma_f32_16x16x32_bf16 v[2:5], v[216:219], v[200:203], v[2:5]
	v_mfma_f32_16x16x32_bf16 v[54:57], v[212:215], v[180:183], v[54:57]
	v_mfma_f32_16x16x32_bf16 v[50:53], v[220:223], v[180:183], v[50:53]
	v_mfma_f32_16x16x32_bf16 v[38:41], v[212:215], v[188:191], v[38:41]
	v_mfma_f32_16x16x32_bf16 v[34:37], v[220:223], v[188:191], v[34:37]
	v_mfma_f32_16x16x32_bf16 v[22:25], v[212:215], v[196:199], v[22:25]
	v_mfma_f32_16x16x32_bf16 v[18:21], v[220:223], v[196:199], v[18:21]
	v_mfma_f32_16x16x32_bf16 v[6:9], v[212:215], v[204:207], v[6:9]
	v_mfma_f32_16x16x32_bf16 v[2:5], v[220:223], v[204:207], v[2:5]
	s_setprio 0
	s_barrier
	ds_read_b128 v[138:141], v155
	ds_read_b128 v[164:167], v156
	ds_read_b128 v[168:171], v157
	ds_read_b128 v[172:175], v158
	s_add_u32 s26, s26, 0x100000
	s_addc_u32 s27, s27, 0
	s_mov_b32 m0, s39
	v_lshl_add_u64 v[208:209], s[26:27], 0, v[132:133]
	ds_read_b128 v[176:179], v145 offset:32768
	ds_read_b128 v[180:183], v145 offset:33792
	ds_read_b128 v[184:187], v145 offset:34816
	ds_read_b128 v[188:191], v145 offset:35840
	ds_read_b128 v[192:195], v145 offset:36864
	ds_read_b128 v[196:199], v145 offset:37888
	ds_read_b128 v[200:203], v145 offset:38912
	ds_read_b128 v[204:207], v145 offset:39936
	global_load_lds_dwordx4 v[208:209], off
	v_lshl_add_u64 v[208:209], s[26:27], 0, v[130:131]
	s_mov_b32 m0, s40
	s_nop 0
	global_load_lds_dwordx4 v[208:209], off
	s_waitcnt lgkmcnt(8)
	s_barrier
	s_waitcnt lgkmcnt(0)
	s_setprio 1
	s_waitcnt lgkmcnt(0)
	v_mfma_f32_16x16x32_bf16 v[126:129], v[138:141], v[176:179], v[126:129]
	v_mfma_f32_16x16x32_bf16 v[122:125], v[168:171], v[176:179], v[122:125]
	v_mfma_f32_16x16x32_bf16 v[114:117], v[138:141], v[184:187], v[114:117]
	v_mfma_f32_16x16x32_bf16 v[106:109], v[168:171], v[184:187], v[106:109]
	v_mfma_f32_16x16x32_bf16 v[94:97], v[138:141], v[192:195], v[94:97]
	v_mfma_f32_16x16x32_bf16 v[90:93], v[168:171], v[192:195], v[90:93]
	v_mfma_f32_16x16x32_bf16 v[78:81], v[138:141], v[200:203], v[78:81]
	v_mfma_f32_16x16x32_bf16 v[74:77], v[168:171], v[200:203], v[74:77]
	v_mfma_f32_16x16x32_bf16 v[126:129], v[164:167], v[180:183], v[126:129]
	v_mfma_f32_16x16x32_bf16 v[122:125], v[172:175], v[180:183], v[122:125]
	v_mfma_f32_16x16x32_bf16 v[114:117], v[164:167], v[188:191], v[114:117]
	v_mfma_f32_16x16x32_bf16 v[106:109], v[172:175], v[188:191], v[106:109]
	v_mfma_f32_16x16x32_bf16 v[94:97], v[164:167], v[196:199], v[94:97]
	v_mfma_f32_16x16x32_bf16 v[90:93], v[172:175], v[196:199], v[90:93]
	v_mfma_f32_16x16x32_bf16 v[78:81], v[164:167], v[204:207], v[78:81]
	v_mfma_f32_16x16x32_bf16 v[74:77], v[172:175], v[204:207], v[74:77]
	s_setprio 0
	s_barrier
	s_mov_b32 m0, s41
	v_lshl_add_u64 v[224:225], v[224:225], 0, s[6:7]
	ds_read_b128 v[208:211], v159
	ds_read_b128 v[212:215], v160
	ds_read_b128 v[216:219], v161
	ds_read_b128 v[220:223], v162
	global_load_lds_dwordx4 v[224:225], off
	v_lshl_add_u64 v[224:225], v[226:227], 0, s[6:7]
	s_mov_b32 m0, s42
	s_nop 0
	global_load_lds_dwordx4 v[224:225], off
	s_barrier
	s_waitcnt lgkmcnt(0)
	s_setprio 1
	s_waitcnt lgkmcnt(0)
	v_mfma_f32_16x16x32_bf16 v[118:121], v[208:211], v[176:179], v[118:121]
	v_mfma_f32_16x16x32_bf16 v[110:113], v[216:219], v[176:179], v[110:113]
	v_mfma_f32_16x16x32_bf16 v[102:105], v[208:211], v[184:187], v[102:105]
	v_mfma_f32_16x16x32_bf16 v[98:101], v[216:219], v[184:187], v[98:101]
	v_mfma_f32_16x16x32_bf16 v[86:89], v[208:211], v[192:195], v[86:89]
	v_mfma_f32_16x16x32_bf16 v[82:85], v[216:219], v[192:195], v[82:85]
	v_mfma_f32_16x16x32_bf16 v[70:73], v[208:211], v[200:203], v[70:73]
	v_mfma_f32_16x16x32_bf16 v[66:69], v[216:219], v[200:203], v[66:69]
	v_mfma_f32_16x16x32_bf16 v[118:121], v[212:215], v[180:183], v[118:121]
	v_mfma_f32_16x16x32_bf16 v[110:113], v[220:223], v[180:183], v[110:113]
	v_mfma_f32_16x16x32_bf16 v[102:105], v[212:215], v[188:191], v[102:105]
	v_mfma_f32_16x16x32_bf16 v[98:101], v[220:223], v[188:191], v[98:101]
	v_mfma_f32_16x16x32_bf16 v[86:89], v[212:215], v[196:199], v[86:89]
	v_mfma_f32_16x16x32_bf16 v[82:85], v[220:223], v[196:199], v[82:85]
	v_mfma_f32_16x16x32_bf16 v[70:73], v[212:215], v[204:207], v[70:73]
	v_mfma_f32_16x16x32_bf16 v[66:69], v[220:223], v[204:207], v[66:69]
	s_setprio 0
	s_mov_b32 m0, s43
	v_lshl_add_u64 v[224:225], v[228:229], 0, s[6:7]
	s_barrier
	ds_read_b128 v[176:179], v145 offset:49152
	ds_read_b128 v[180:183], v145 offset:50176
	ds_read_b128 v[184:187], v145 offset:51200
	ds_read_b128 v[188:191], v145 offset:52224
	ds_read_b128 v[192:195], v145 offset:53248
	ds_read_b128 v[196:199], v145 offset:54272
	ds_read_b128 v[200:203], v145 offset:55296
	ds_read_b128 v[204:207], v145 offset:56320
	global_load_lds_dwordx4 v[224:225], off
	v_lshl_add_u64 v[224:225], v[230:231], 0, s[6:7]
	s_mov_b32 m0, s44
	s_nop 0
	global_load_lds_dwordx4 v[224:225], off
	s_barrier
; #define PG8_STAGE(bufoff, gbase, voff) do { _Pragma("unroll") for (int _i = 0; _i < 2; ++_i) \
;         __builtin_amdgcn_global_load_lds((const unsigned*)((const char*)(gbase) + (voff)[_i]), (PG8_LAS unsigned*)(lds + (bufoff) + ldsw + _i * 8192), 16, 0, 0); } while (0)
; #define PG8_MMA(ai, bj, At, Bt) do { __builtin_amdgcn_s_setprio(1); _Pragma("unroll") for (int m = 0; m < 4; ++m) _Pragma("unroll") for (int n = 0; n < 2; ++n) _Pragma("unroll") for (int k = 0; k < 2; ++k) \
;         acc[ai][bj][m][n] = __builtin_amdgcn_mfma_f32_16x16x32_bf16(Bt[n][k], At[m][k], acc[ai][bj][m][n], 0, 0, 0); __builtin_amdgcn_s_setprio(0); } while (0)
; #define PG8_WAIT_V(n) asm volatile("s_waitcnt vmcnt(" #n ")" ::: "memory")
; #define PG8_WAIT_L(n) asm volatile("s_waitcnt lgkmcnt(" #n ")" ::: "memory")
; #define PG8_BAR __builtin_amdgcn_s_barrier()
; #define PG8_SCHED __builtin_amdgcn_sched_barrier(0)
; template <class Epi, class Sched>
; __device__ __forceinline__ void gemm_phase(PG8_LAS unsigned char* lds, const Gemm g, const Sched& S, const Epi& E) {
;     ...
;             PG8_BAR; PG8_WAIT_L(0); PG8_MMA(1, 0, At, B0); PG8_BAR; PG8_SCHED;
;             PG8_STAGE(PG8_SB(1, 1), b3 + hstep, voffB);
;             PG8_WAIT_V(6); PG8_BAR; PG8_MMA(1, 1, At, B1); PG8_BAR;
;   __device__ __forceinline__ void operator()(const acc8_t& acc, const pg8::Unit& u, int wr, int wc, int fr, int fq) const {
; #pragma unroll
;     for (int ai = 0; ai < 2; ai++)
; #pragma unroll
;       for (int m = 0; m < 4; m++) {
;         const size_t token = EPI_TOKEN(u, ai, m);
; #pragma unroll
;         for (int bj = 0; bj < 2; bj++)
; #pragma unroll
;           for (int n = 0; n < 2; n++) {
;             float* yp = out + O_Y + token * 1024 + EPI_COL(u, bj, n);
;             float4 y = *(const float4*)yp;
;             y.x += acc[ai][bj][m][n][0]; y.y += acc[ai][bj][m][n][1]; y.z += acc[ai][bj][m][n][2]; y.w += acc[ai][bj][m][n][3];
;             *(float4*)yp = y;
;           }
	s_waitcnt lgkmcnt(0)
	s_setprio 1
	s_waitcnt lgkmcnt(0)
	v_mfma_f32_16x16x32_bf16 v[62:65], v[138:141], v[176:179], v[62:65]
	v_mfma_f32_16x16x32_bf16 v[58:61], v[168:171], v[176:179], v[58:61]
	v_mfma_f32_16x16x32_bf16 v[46:49], v[138:141], v[184:187], v[46:49]
	v_mfma_f32_16x16x32_bf16 v[42:45], v[168:171], v[184:187], v[42:45]
	v_mfma_f32_16x16x32_bf16 v[30:33], v[138:141], v[192:195], v[30:33]
	v_mfma_f32_16x16x32_bf16 v[26:29], v[168:171], v[192:195], v[26:29]
	v_mfma_f32_16x16x32_bf16 v[14:17], v[138:141], v[200:203], v[14:17]
	v_mfma_f32_16x16x32_bf16 v[10:13], v[168:171], v[200:203], v[10:13]
	v_mfma_f32_16x16x32_bf16 v[62:65], v[164:167], v[180:183], v[62:65]
	v_mfma_f32_16x16x32_bf16 v[58:61], v[172:175], v[180:183], v[58:61]
	v_mfma_f32_16x16x32_bf16 v[46:49], v[164:167], v[188:191], v[46:49]
	v_mfma_f32_16x16x32_bf16 v[42:45], v[172:175], v[188:191], v[42:45]
	v_mfma_f32_16x16x32_bf16 v[30:33], v[164:167], v[196:199], v[30:33]
	v_mfma_f32_16x16x32_bf16 v[26:29], v[172:175], v[196:199], v[26:29]
	v_mfma_f32_16x16x32_bf16 v[14:17], v[164:167], v[204:207], v[14:17]
	v_mfma_f32_16x16x32_bf16 v[10:13], v[172:175], v[204:207], v[10:13]
	s_setprio 0
	s_barrier
	s_add_u32 s24, s24, 0x100080
	s_addc_u32 s25, s25, 0
	s_mov_b32 m0, s45
	v_lshl_add_u64 v[138:139], s[24:25], 0, v[132:133]
	global_load_lds_dwordx4 v[138:139], off
	v_lshl_add_u64 v[138:139], s[24:25], 0, v[130:131]
	s_mov_b32 m0, s46
	s_nop 0
	global_load_lds_dwordx4 v[138:139], off
	s_waitcnt vmcnt(6)
	s_barrier
	s_setprio 1
	v_mfma_f32_16x16x32_bf16 v[54:57], v[208:211], v[176:179], v[54:57]
	v_mfma_f32_16x16x32_bf16 v[50:53], v[216:219], v[176:179], v[50:53]
	v_mfma_f32_16x16x32_bf16 v[38:41], v[208:211], v[184:187], v[38:41]
	v_mfma_f32_16x16x32_bf16 v[34:37], v[216:219], v[184:187], v[34:37]
	v_mfma_f32_16x16x32_bf16 v[22:25], v[208:211], v[192:195], v[22:25]
	v_mfma_f32_16x16x32_bf16 v[18:21], v[216:219], v[192:195], v[18:21]
	v_mfma_f32_16x16x32_bf16 v[6:9], v[208:211], v[200:203], v[6:9]
	v_mfma_f32_16x16x32_bf16 v[2:5], v[216:219], v[200:203], v[2:5]
	v_mfma_f32_16x16x32_bf16 v[54:57], v[212:215], v[180:183], v[54:57]
	v_mfma_f32_16x16x32_bf16 v[50:53], v[220:223], v[180:183], v[50:53]
	v_mfma_f32_16x16x32_bf16 v[38:41], v[212:215], v[188:191], v[38:41]
	v_mfma_f32_16x16x32_bf16 v[34:37], v[220:223], v[188:191], v[34:37]
	v_mfma_f32_16x16x32_bf16 v[22:25], v[212:215], v[196:199], v[22:25]
	v_mfma_f32_16x16x32_bf16 v[18:21], v[220:223], v[196:199], v[18:21]
	v_mfma_f32_16x16x32_bf16 v[6:9], v[212:215], v[204:207], v[6:9]
	v_mfma_f32_16x16x32_bf16 v[2:5], v[220:223], v[204:207], v[2:5]
	s_setprio 0
	s_add_i32 s54, s54, 2
	s_add_u32 s22, s22, 0x100
	s_addc_u32 s23, s23, 0
	s_add_u32 s52, s52, 0x100
	s_addc_u32 s53, s53, 0
	s_cmp_gt_u32 s54, 61
	s_barrier
	s_cbranch_scc0 .LBB0_828
	v_lshl_or_b32 v138, s18, 8, v146
	v_and_b32_e32 v140, -9, v144
	v_bfe_u32 v214, v144, 3, 1
	v_lshl_add_u32 v140, s20, 8, v140
	v_ashrrev_i32_e32 v139, 31, v138
	v_ashrrev_i32_e32 v141, 31, v140
	v_lshlrev_b64 v[138:139], 2, v[138:139]
	v_lshlrev_b64 v[140:141], 12, v[140:141]
	v_lshlrev_b32_e32 v214, 6, v214
	v_mov_b32_e32 v215, 0
	v_lshl_add_u64 v[138:139], v[138:139], 0, v[214:215]
	v_lshl_add_u64 v[140:141], s[86:87], 0, v[140:141]
	v_lshl_add_u64 v[138:139], v[140:141], 0, v[138:139]
	s_mov_b64 s[62:63], 0x8000
	v_lshl_add_u64 v[140:141], v[138:139], 0, s[62:63]
	v_mov_b64_e32 v[212:213], v[138:139]
	v_mov_b64_e32 v[232:233], v[140:141]
	s_mov_b32 s60, 0xff00ff00
	s_mov_b32 s61, 0xff00ff00
	s_mov_b32 s18, s8
	s_mov_b32 s20, s10
	s_mov_b64 s[24:25], s[16:17]
	s_mov_b64 s[22:23], s[14:15]
	global_load_dwordx4 v[164:167], v[138:139], off nt
	global_load_dwordx4 v[168:171], v[138:139], off offset:512 nt
	global_load_dwordx4 v[172:175], v[140:141], off nt
	global_load_dwordx4 v[176:179], v[140:141], off offset:512 nt
	s_mov_b64 s[62:63], 0x10000
	v_lshl_add_u64 v[138:139], v[138:139], 0, s[62:63]
	v_lshl_add_u64 v[140:141], v[140:141], 0, s[62:63]
	global_load_dwordx4 v[180:183], v[138:139], off nt
	global_load_dwordx4 v[184:187], v[138:139], off offset:512 nt
	global_load_dwordx4 v[188:191], v[140:141], off nt
	global_load_dwordx4 v[192:195], v[140:141], off offset:512 nt
	v_mov_b32_dpp v228, v122 row_ror:8 row_mask:0xf bank_mask:0xf
	v_mov_b32_dpp v229, v123 row_ror:8 row_mask:0xf bank_mask:0xf
	v_mov_b32_dpp v230, v124 row_ror:8 row_mask:0xf bank_mask:0xf
	v_mov_b32_dpp v231, v125 row_ror:8 row_mask:0xf bank_mask:0xf
	v_mov_b32_dpp v234, v126 row_ror:8 row_mask:0xf bank_mask:0xf
	v_mov_b32_dpp v235, v127 row_ror:8 row_mask:0xf bank_mask:0xf
	v_mov_b32_dpp v236, v128 row_ror:8 row_mask:0xf bank_mask:0xf
	v_mov_b32_dpp v237, v129 row_ror:8 row_mask:0xf bank_mask:0xf
	v_cndmask_b32_e64 v126, v126, v228, s[60:61]
	v_cndmask_b32_e64 v127, v127, v229, s[60:61]
	v_cndmask_b32_e64 v128, v128, v230, s[60:61]
	v_cndmask_b32_e64 v129, v129, v231, s[60:61]
	v_cndmask_b32_e64 v122, v234, v122, s[60:61]
	v_cndmask_b32_e64 v123, v235, v123, s[60:61]
	v_cndmask_b32_e64 v124, v236, v124, s[60:61]
	v_cndmask_b32_e64 v125, v237, v125, s[60:61]
	v_mov_b32_dpp v228, v110 row_ror:8 row_mask:0xf bank_mask:0xf
	v_mov_b32_dpp v229, v111 row_ror:8 row_mask:0xf bank_mask:0xf
	v_mov_b32_dpp v230, v112 row_ror:8 row_mask:0xf bank_mask:0xf
	v_mov_b32_dpp v231, v113 row_ror:8 row_mask:0xf bank_mask:0xf
	v_mov_b32_dpp v234, v118 row_ror:8 row_mask:0xf bank_mask:0xf
	v_mov_b32_dpp v235, v119 row_ror:8 row_mask:0xf bank_mask:0xf
	v_mov_b32_dpp v236, v120 row_ror:8 row_mask:0xf bank_mask:0xf
	v_mov_b32_dpp v237, v121 row_ror:8 row_mask:0xf bank_mask:0xf
	v_cndmask_b32_e64 v118, v118, v228, s[60:61]
	v_cndmask_b32_e64 v119, v119, v229, s[60:61]
	v_cndmask_b32_e64 v120, v120, v230, s[60:61]
	v_cndmask_b32_e64 v121, v121, v231, s[60:61]
	v_cndmask_b32_e64 v110, v234, v110, s[60:61]
	v_cndmask_b32_e64 v111, v235, v111, s[60:61]
	v_cndmask_b32_e64 v112, v236, v112, s[60:61]
	v_cndmask_b32_e64 v113, v237, v113, s[60:61]
	s_mov_b64 s[62:63], 0x10000
	v_lshl_add_u64 v[138:139], v[138:139], 0, s[62:63]
	v_lshl_add_u64 v[140:141], v[140:141], 0, s[62:63]
	global_load_dwordx4 v[196:199], v[138:139], off nt
	global_load_dwordx4 v[200:203], v[138:139], off offset:512 nt
	global_load_dwordx4 v[204:207], v[140:141], off nt
	global_load_dwordx4 v[208:211], v[140:141], off offset:512 nt
	s_waitcnt vmcnt(8)
;   __device__ __forceinline__ void operator()(const acc8_t& acc, const pg8::Unit& u, int wr, int wc, int fr, int fq) const {
;     ...
;     for (int ai = 0; ai < 2; ai++)
; #pragma unroll
;       for (int m = 0; m < 4; m++) {
;         const size_t token = EPI_TOKEN(u, ai, m);
; #pragma unroll
;         for (int bj = 0; bj < 2; bj++)
; #pragma unroll
;           for (int n = 0; n < 2; n++) {
;             float* yp = out + O_Y + token * 1024 + EPI_COL(u, bj, n);
;             float4 y = *(const float4*)yp;
;             y.x += acc[ai][bj][m][n][0]; y.y += acc[ai][bj][m][n][1]; y.z += acc[ai][bj][m][n][2]; y.w += acc[ai][bj][m][n][3];
;             *(float4*)yp = y;
;           }
	v_pk_add_f32 v[164:165], v[126:127], v[164:165]
	v_pk_add_f32 v[166:167], v[128:129], v[166:167]
	v_pk_add_f32 v[172:173], v[122:123], v[172:173]
	v_pk_add_f32 v[174:175], v[124:125], v[174:175]
	v_pk_add_f32 v[168:169], v[118:119], v[168:169]
	v_pk_add_f32 v[170:171], v[120:121], v[170:171]
	v_pk_add_f32 v[176:177], v[110:111], v[176:177]
	v_pk_add_f32 v[178:179], v[112:113], v[178:179]
	global_store_dwordx4 v[212:213], v[164:167], off
	global_store_dwordx4 v[212:213], v[168:171], off offset:512
	global_store_dwordx4 v[232:233], v[172:175], off
	global_store_dwordx4 v[232:233], v[176:179], off offset:512
	s_mov_b64 s[62:63], 0x10000
	v_lshl_add_u64 v[212:213], v[212:213], 0, s[62:63]
	v_lshl_add_u64 v[232:233], v[232:233], 0, s[62:63]
	v_mov_b32_dpp v228, v106 row_ror:8 row_mask:0xf bank_mask:0xf
	v_mov_b32_dpp v229, v107 row_ror:8 row_mask:0xf bank_mask:0xf
	v_mov_b32_dpp v230, v108 row_ror:8 row_mask:0xf bank_mask:0xf
	v_mov_b32_dpp v231, v109 row_ror:8 row_mask:0xf bank_mask:0xf
	v_mov_b32_dpp v234, v114 row_ror:8 row_mask:0xf bank_mask:0xf
	v_mov_b32_dpp v235, v115 row_ror:8 row_mask:0xf bank_mask:0xf
	v_mov_b32_dpp v236, v116 row_ror:8 row_mask:0xf bank_mask:0xf
	v_mov_b32_dpp v237, v117 row_ror:8 row_mask:0xf bank_mask:0xf
	v_cndmask_b32_e64 v114, v114, v228, s[60:61]
	v_cndmask_b32_e64 v115, v115, v229, s[60:61]
	v_cndmask_b32_e64 v116, v116, v230, s[60:61]
	v_cndmask_b32_e64 v117, v117, v231, s[60:61]
	v_cndmask_b32_e64 v106, v234, v106, s[60:61]
	v_cndmask_b32_e64 v107, v235, v107, s[60:61]
	v_cndmask_b32_e64 v108, v236, v108, s[60:61]
	v_cndmask_b32_e64 v109, v237, v109, s[60:61]
	v_mov_b32_dpp v228, v98 row_ror:8 row_mask:0xf bank_mask:0xf
	v_mov_b32_dpp v229, v99 row_ror:8 row_mask:0xf bank_mask:0xf
	v_mov_b32_dpp v230, v100 row_ror:8 row_mask:0xf bank_mask:0xf
	v_mov_b32_dpp v231, v101 row_ror:8 row_mask:0xf bank_mask:0xf
	v_mov_b32_dpp v234, v102 row_ror:8 row_mask:0xf bank_mask:0xf
	v_mov_b32_dpp v235, v103 row_ror:8 row_mask:0xf bank_mask:0xf
	v_mov_b32_dpp v236, v104 row_ror:8 row_mask:0xf bank_mask:0xf
	v_mov_b32_dpp v237, v105 row_ror:8 row_mask:0xf bank_mask:0xf
	v_cndmask_b32_e64 v102, v102, v228, s[60:61]
	v_cndmask_b32_e64 v103, v103, v229, s[60:61]
	v_cndmask_b32_e64 v104, v104, v230, s[60:61]
	v_cndmask_b32_e64 v105, v105, v231, s[60:61]
	v_cndmask_b32_e64 v98, v234, v98, s[60:61]
	v_cndmask_b32_e64 v99, v235, v99, s[60:61]
	v_cndmask_b32_e64 v100, v236, v100, s[60:61]
	v_cndmask_b32_e64 v101, v237, v101, s[60:61]
	s_mov_b64 s[62:63], 0x10000
	v_lshl_add_u64 v[138:139], v[138:139], 0, s[62:63]
	v_lshl_add_u64 v[140:141], v[140:141], 0, s[62:63]
	global_load_dwordx4 v[164:167], v[138:139], off nt
	global_load_dwordx4 v[168:171], v[138:139], off offset:512 nt
	global_load_dwordx4 v[172:175], v[140:141], off nt
	global_load_dwordx4 v[176:179], v[140:141], off offset:512 nt
	s_waitcnt vmcnt(12)
	v_pk_add_f32 v[180:181], v[114:115], v[180:181]
	v_pk_add_f32 v[182:183], v[116:117], v[182:183]
	v_pk_add_f32 v[188:189], v[106:107], v[188:189]
	v_pk_add_f32 v[190:191], v[108:109], v[190:191]
	v_pk_add_f32 v[184:185], v[102:103], v[184:185]
	v_pk_add_f32 v[186:187], v[104:105], v[186:187]
	v_pk_add_f32 v[192:193], v[98:99], v[192:193]
	v_pk_add_f32 v[194:195], v[100:101], v[194:195]
	global_store_dwordx4 v[212:213], v[180:183], off
	global_store_dwordx4 v[212:213], v[184:187], off offset:512
	global_store_dwordx4 v[232:233], v[188:191], off
	global_store_dwordx4 v[232:233], v[192:195], off offset:512
	s_mov_b64 s[62:63], 0x10000
	v_lshl_add_u64 v[212:213], v[212:213], 0, s[62:63]
	v_lshl_add_u64 v[232:233], v[232:233], 0, s[62:63]
	v_mov_b32_dpp v228, v90 row_ror:8 row_mask:0xf bank_mask:0xf
	v_mov_b32_dpp v229, v91 row_ror:8 row_mask:0xf bank_mask:0xf
	v_mov_b32_dpp v230, v92 row_ror:8 row_mask:0xf bank_mask:0xf
	v_mov_b32_dpp v231, v93 row_ror:8 row_mask:0xf bank_mask:0xf
	v_mov_b32_dpp v234, v94 row_ror:8 row_mask:0xf bank_mask:0xf
	v_mov_b32_dpp v235, v95 row_ror:8 row_mask:0xf bank_mask:0xf
	v_mov_b32_dpp v236, v96 row_ror:8 row_mask:0xf bank_mask:0xf
	v_mov_b32_dpp v237, v97 row_ror:8 row_mask:0xf bank_mask:0xf
	v_cndmask_b32_e64 v94, v94, v228, s[60:61]
	v_cndmask_b32_e64 v95, v95, v229, s[60:61]
	v_cndmask_b32_e64 v96, v96, v230, s[60:61]
	v_cndmask_b32_e64 v97, v97, v231, s[60:61]
	v_cndmask_b32_e64 v90, v234, v90, s[60:61]
	v_cndmask_b32_e64 v91, v235, v91, s[60:61]
	v_cndmask_b32_e64 v92, v236, v92, s[60:61]
	v_cndmask_b32_e64 v93, v237, v93, s[60:61]
	v_mov_b32_dpp v228, v82 row_ror:8 row_mask:0xf bank_mask:0xf
	v_mov_b32_dpp v229, v83 row_ror:8 row_mask:0xf bank_mask:0xf
	v_mov_b32_dpp v230, v84 row_ror:8 row_mask:0xf bank_mask:0xf
	v_mov_b32_dpp v231, v85 row_ror:8 row_mask:0xf bank_mask:0xf
	v_mov_b32_dpp v234, v86 row_ror:8 row_mask:0xf bank_mask:0xf
	v_mov_b32_dpp v235, v87 row_ror:8 row_mask:0xf bank_mask:0xf
	v_mov_b32_dpp v236, v88 row_ror:8 row_mask:0xf bank_mask:0xf
	v_mov_b32_dpp v237, v89 row_ror:8 row_mask:0xf bank_mask:0xf
	v_cndmask_b32_e64 v86, v86, v228, s[60:61]
	v_cndmask_b32_e64 v87, v87, v229, s[60:61]
	v_cndmask_b32_e64 v88, v88, v230, s[60:61]
	v_cndmask_b32_e64 v89, v89, v231, s[60:61]
	v_cndmask_b32_e64 v82, v234, v82, s[60:61]
	v_cndmask_b32_e64 v83, v235, v83, s[60:61]
	v_cndmask_b32_e64 v84, v236, v84, s[60:61]
	v_cndmask_b32_e64 v85, v237, v85, s[60:61]
	s_mov_b64 s[62:63], 0x50000
	v_lshl_add_u64 v[138:139], v[138:139], 0, s[62:63]
	v_lshl_add_u64 v[140:141], v[140:141], 0, s[62:63]
	global_load_dwordx4 v[180:183], v[138:139], off nt
	global_load_dwordx4 v[184:187], v[138:139], off offset:512 nt
	global_load_dwordx4 v[188:191], v[140:141], off nt
	global_load_dwordx4 v[192:195], v[140:141], off offset:512 nt
	s_waitcnt vmcnt(16)
;   __device__ __forceinline__ void operator()(const acc8_t& acc, const pg8::Unit& u, int wr, int wc, int fr, int fq) const {
;     ...
;     for (int ai = 0; ai < 2; ai++)
; #pragma unroll
;       for (int m = 0; m < 4; m++) {
;         const size_t token = EPI_TOKEN(u, ai, m);
; #pragma unroll
;         for (int bj = 0; bj < 2; bj++)
; #pragma unroll
;           for (int n = 0; n < 2; n++) {
;             float* yp = out + O_Y + token * 1024 + EPI_COL(u, bj, n);
;             float4 y = *(const float4*)yp;
;             y.x += acc[ai][bj][m][n][0]; y.y += acc[ai][bj][m][n][1]; y.z += acc[ai][bj][m][n][2]; y.w += acc[ai][bj][m][n][3];
;             *(float4*)yp = y;
;           }
	v_pk_add_f32 v[196:197], v[94:95], v[196:197]
	v_pk_add_f32 v[198:199], v[96:97], v[198:199]
	v_pk_add_f32 v[204:205], v[90:91], v[204:205]
	v_pk_add_f32 v[206:207], v[92:93], v[206:207]
	v_pk_add_f32 v[200:201], v[86:87], v[200:201]
	v_pk_add_f32 v[202:203], v[88:89], v[202:203]
	v_pk_add_f32 v[208:209], v[82:83], v[208:209]
	v_pk_add_f32 v[210:211], v[84:85], v[210:211]
	global_store_dwordx4 v[212:213], v[196:199], off
	global_store_dwordx4 v[212:213], v[200:203], off offset:512
	global_store_dwordx4 v[232:233], v[204:207], off
	global_store_dwordx4 v[232:233], v[208:211], off offset:512
	s_mov_b64 s[62:63], 0x10000
	v_lshl_add_u64 v[212:213], v[212:213], 0, s[62:63]
	v_lshl_add_u64 v[232:233], v[232:233], 0, s[62:63]
	v_mov_b32_dpp v228, v74 row_ror:8 row_mask:0xf bank_mask:0xf
	v_mov_b32_dpp v229, v75 row_ror:8 row_mask:0xf bank_mask:0xf
	v_mov_b32_dpp v230, v76 row_ror:8 row_mask:0xf bank_mask:0xf
	v_mov_b32_dpp v231, v77 row_ror:8 row_mask:0xf bank_mask:0xf
	v_mov_b32_dpp v234, v78 row_ror:8 row_mask:0xf bank_mask:0xf
	v_mov_b32_dpp v235, v79 row_ror:8 row_mask:0xf bank_mask:0xf
	v_mov_b32_dpp v236, v80 row_ror:8 row_mask:0xf bank_mask:0xf
	v_mov_b32_dpp v237, v81 row_ror:8 row_mask:0xf bank_mask:0xf
	v_cndmask_b32_e64 v78, v78, v228, s[60:61]
	v_cndmask_b32_e64 v79, v79, v229, s[60:61]
	v_cndmask_b32_e64 v80, v80, v230, s[60:61]
	v_cndmask_b32_e64 v81, v81, v231, s[60:61]
	v_cndmask_b32_e64 v74, v234, v74, s[60:61]
	v_cndmask_b32_e64 v75, v235, v75, s[60:61]
	v_cndmask_b32_e64 v76, v236, v76, s[60:61]
	v_cndmask_b32_e64 v77, v237, v77, s[60:61]
	v_mov_b32_dpp v228, v66 row_ror:8 row_mask:0xf bank_mask:0xf
	v_mov_b32_dpp v229, v67 row_ror:8 row_mask:0xf bank_mask:0xf
	v_mov_b32_dpp v230, v68 row_ror:8 row_mask:0xf bank_mask:0xf
	v_mov_b32_dpp v231, v69 row_ror:8 row_mask:0xf bank_mask:0xf
	v_mov_b32_dpp v234, v70 row_ror:8 row_mask:0xf bank_mask:0xf
	v_mov_b32_dpp v235, v71 row_ror:8 row_mask:0xf bank_mask:0xf
	v_mov_b32_dpp v236, v72 row_ror:8 row_mask:0xf bank_mask:0xf
	v_mov_b32_dpp v237, v73 row_ror:8 row_mask:0xf bank_mask:0xf
	v_cndmask_b32_e64 v70, v70, v228, s[60:61]
	v_cndmask_b32_e64 v71, v71, v229, s[60:61]
	v_cndmask_b32_e64 v72, v72, v230, s[60:61]
	v_cndmask_b32_e64 v73, v73, v231, s[60:61]
	v_cndmask_b32_e64 v66, v234, v66, s[60:61]
	v_cndmask_b32_e64 v67, v235, v67, s[60:61]
	v_cndmask_b32_e64 v68, v236, v68, s[60:61]
	v_cndmask_b32_e64 v69, v237, v69, s[60:61]
	s_mov_b64 s[62:63], 0x10000
	v_lshl_add_u64 v[138:139], v[138:139], 0, s[62:63]
	v_lshl_add_u64 v[140:141], v[140:141], 0, s[62:63]
	global_load_dwordx4 v[196:199], v[138:139], off nt
	global_load_dwordx4 v[200:203], v[138:139], off offset:512 nt
	global_load_dwordx4 v[204:207], v[140:141], off nt
	global_load_dwordx4 v[208:211], v[140:141], off offset:512 nt
	s_waitcnt vmcnt(16)
	v_pk_add_f32 v[164:165], v[78:79], v[164:165]
	v_pk_add_f32 v[166:167], v[80:81], v[166:167]
	v_pk_add_f32 v[172:173], v[74:75], v[172:173]
	v_pk_add_f32 v[174:175], v[76:77], v[174:175]
	v_pk_add_f32 v[168:169], v[70:71], v[168:169]
	v_pk_add_f32 v[170:171], v[72:73], v[170:171]
	v_pk_add_f32 v[176:177], v[66:67], v[176:177]
	v_pk_add_f32 v[178:179], v[68:69], v[178:179]
	global_store_dwordx4 v[212:213], v[164:167], off
	global_store_dwordx4 v[212:213], v[168:171], off offset:512
	global_store_dwordx4 v[232:233], v[172:175], off
	global_store_dwordx4 v[232:233], v[176:179], off offset:512
	s_mov_b64 s[62:63], 0x50000
	v_lshl_add_u64 v[212:213], v[212:213], 0, s[62:63]
	v_lshl_add_u64 v[232:233], v[232:233], 0, s[62:63]
	v_mov_b32_dpp v228, v58 row_ror:8 row_mask:0xf bank_mask:0xf
	v_mov_b32_dpp v229, v59 row_ror:8 row_mask:0xf bank_mask:0xf
	v_mov_b32_dpp v230, v60 row_ror:8 row_mask:0xf bank_mask:0xf
	v_mov_b32_dpp v231, v61 row_ror:8 row_mask:0xf bank_mask:0xf
	v_mov_b32_dpp v234, v62 row_ror:8 row_mask:0xf bank_mask:0xf
	v_mov_b32_dpp v235, v63 row_ror:8 row_mask:0xf bank_mask:0xf
	v_mov_b32_dpp v236, v64 row_ror:8 row_mask:0xf bank_mask:0xf
	v_mov_b32_dpp v237, v65 row_ror:8 row_mask:0xf bank_mask:0xf
	v_cndmask_b32_e64 v62, v62, v228, s[60:61]
	v_cndmask_b32_e64 v63, v63, v229, s[60:61]
	v_cndmask_b32_e64 v64, v64, v230, s[60:61]
	v_cndmask_b32_e64 v65, v65, v231, s[60:61]
	v_cndmask_b32_e64 v58, v234, v58, s[60:61]
	v_cndmask_b32_e64 v59, v235, v59, s[60:61]
	v_cndmask_b32_e64 v60, v236, v60, s[60:61]
	v_cndmask_b32_e64 v61, v237, v61, s[60:61]
	v_mov_b32_dpp v228, v50 row_ror:8 row_mask:0xf bank_mask:0xf
	v_mov_b32_dpp v229, v51 row_ror:8 row_mask:0xf bank_mask:0xf
	v_mov_b32_dpp v230, v52 row_ror:8 row_mask:0xf bank_mask:0xf
	v_mov_b32_dpp v231, v53 row_ror:8 row_mask:0xf bank_mask:0xf
	v_mov_b32_dpp v234, v54 row_ror:8 row_mask:0xf bank_mask:0xf
	v_mov_b32_dpp v235, v55 row_ror:8 row_mask:0xf bank_mask:0xf
	v_mov_b32_dpp v236, v56 row_ror:8 row_mask:0xf bank_mask:0xf
	v_mov_b32_dpp v237, v57 row_ror:8 row_mask:0xf bank_mask:0xf
	v_cndmask_b32_e64 v54, v54, v228, s[60:61]
	v_cndmask_b32_e64 v55, v55, v229, s[60:61]
	v_cndmask_b32_e64 v56, v56, v230, s[60:61]
	v_cndmask_b32_e64 v57, v57, v231, s[60:61]
	v_cndmask_b32_e64 v50, v234, v50, s[60:61]
	v_cndmask_b32_e64 v51, v235, v51, s[60:61]
	v_cndmask_b32_e64 v52, v236, v52, s[60:61]
	v_cndmask_b32_e64 v53, v237, v53, s[60:61]
	s_mov_b64 s[62:63], 0x10000
	v_lshl_add_u64 v[138:139], v[138:139], 0, s[62:63]
	v_lshl_add_u64 v[140:141], v[140:141], 0, s[62:63]
	global_load_dwordx4 v[164:167], v[138:139], off nt
	global_load_dwordx4 v[168:171], v[138:139], off offset:512 nt
	global_load_dwordx4 v[172:175], v[140:141], off nt
	global_load_dwordx4 v[176:179], v[140:141], off offset:512 nt
	s_waitcnt vmcnt(16)
;   __device__ __forceinline__ void operator()(const acc8_t& acc, const pg8::Unit& u, int wr, int wc, int fr, int fq) const {
;     ...
;     for (int ai = 0; ai < 2; ai++)
; #pragma unroll
;       for (int m = 0; m < 4; m++) {
;         const size_t token = EPI_TOKEN(u, ai, m);
; #pragma unroll
;         for (int bj = 0; bj < 2; bj++)
; #pragma unroll
;           for (int n = 0; n < 2; n++) {
;             float* yp = out + O_Y + token * 1024 + EPI_COL(u, bj, n);
;             float4 y = *(const float4*)yp;
;             y.x += acc[ai][bj][m][n][0]; y.y += acc[ai][bj][m][n][1]; y.z += acc[ai][bj][m][n][2]; y.w += acc[ai][bj][m][n][3];
;             *(float4*)yp = y;
;           }
	v_pk_add_f32 v[180:181], v[62:63], v[180:181]
	v_pk_add_f32 v[182:183], v[64:65], v[182:183]
	v_pk_add_f32 v[188:189], v[58:59], v[188:189]
	v_pk_add_f32 v[190:191], v[60:61], v[190:191]
	v_pk_add_f32 v[184:185], v[54:55], v[184:185]
	v_pk_add_f32 v[186:187], v[56:57], v[186:187]
	v_pk_add_f32 v[192:193], v[50:51], v[192:193]
	v_pk_add_f32 v[194:195], v[52:53], v[194:195]
	global_store_dwordx4 v[212:213], v[180:183], off
	global_store_dwordx4 v[212:213], v[184:187], off offset:512
	global_store_dwordx4 v[232:233], v[188:191], off
	global_store_dwordx4 v[232:233], v[192:195], off offset:512
	s_mov_b64 s[62:63], 0x10000
	v_lshl_add_u64 v[212:213], v[212:213], 0, s[62:63]
	v_lshl_add_u64 v[232:233], v[232:233], 0, s[62:63]
	v_mov_b32_dpp v228, v42 row_ror:8 row_mask:0xf bank_mask:0xf
	v_mov_b32_dpp v229, v43 row_ror:8 row_mask:0xf bank_mask:0xf
	v_mov_b32_dpp v230, v44 row_ror:8 row_mask:0xf bank_mask:0xf
	v_mov_b32_dpp v231, v45 row_ror:8 row_mask:0xf bank_mask:0xf
	v_mov_b32_dpp v234, v46 row_ror:8 row_mask:0xf bank_mask:0xf
	v_mov_b32_dpp v235, v47 row_ror:8 row_mask:0xf bank_mask:0xf
	v_mov_b32_dpp v236, v48 row_ror:8 row_mask:0xf bank_mask:0xf
	v_mov_b32_dpp v237, v49 row_ror:8 row_mask:0xf bank_mask:0xf
	v_cndmask_b32_e64 v46, v46, v228, s[60:61]
	v_cndmask_b32_e64 v47, v47, v229, s[60:61]
	v_cndmask_b32_e64 v48, v48, v230, s[60:61]
	v_cndmask_b32_e64 v49, v49, v231, s[60:61]
	v_cndmask_b32_e64 v42, v234, v42, s[60:61]
	v_cndmask_b32_e64 v43, v235, v43, s[60:61]
	v_cndmask_b32_e64 v44, v236, v44, s[60:61]
	v_cndmask_b32_e64 v45, v237, v45, s[60:61]
	v_mov_b32_dpp v228, v34 row_ror:8 row_mask:0xf bank_mask:0xf
	v_mov_b32_dpp v229, v35 row_ror:8 row_mask:0xf bank_mask:0xf
	v_mov_b32_dpp v230, v36 row_ror:8 row_mask:0xf bank_mask:0xf
	v_mov_b32_dpp v231, v37 row_ror:8 row_mask:0xf bank_mask:0xf
	v_mov_b32_dpp v234, v38 row_ror:8 row_mask:0xf bank_mask:0xf
	v_mov_b32_dpp v235, v39 row_ror:8 row_mask:0xf bank_mask:0xf
	v_mov_b32_dpp v236, v40 row_ror:8 row_mask:0xf bank_mask:0xf
	v_mov_b32_dpp v237, v41 row_ror:8 row_mask:0xf bank_mask:0xf
	v_cndmask_b32_e64 v38, v38, v228, s[60:61]
	v_cndmask_b32_e64 v39, v39, v229, s[60:61]
	v_cndmask_b32_e64 v40, v40, v230, s[60:61]
	v_cndmask_b32_e64 v41, v41, v231, s[60:61]
	v_cndmask_b32_e64 v34, v234, v34, s[60:61]
	v_cndmask_b32_e64 v35, v235, v35, s[60:61]
	v_cndmask_b32_e64 v36, v236, v36, s[60:61]
	v_cndmask_b32_e64 v37, v237, v37, s[60:61]
	s_mov_b64 s[62:63], 0x10000
	v_lshl_add_u64 v[138:139], v[138:139], 0, s[62:63]
	v_lshl_add_u64 v[140:141], v[140:141], 0, s[62:63]
	global_load_dwordx4 v[180:183], v[138:139], off nt
	global_load_dwordx4 v[184:187], v[138:139], off offset:512 nt
	global_load_dwordx4 v[188:191], v[140:141], off nt
	global_load_dwordx4 v[192:195], v[140:141], off offset:512 nt
	s_waitcnt vmcnt(16)
	v_pk_add_f32 v[196:197], v[46:47], v[196:197]
	v_pk_add_f32 v[198:199], v[48:49], v[198:199]
	v_pk_add_f32 v[204:205], v[42:43], v[204:205]
	v_pk_add_f32 v[206:207], v[44:45], v[206:207]
	v_pk_add_f32 v[200:201], v[38:39], v[200:201]
	v_pk_add_f32 v[202:203], v[40:41], v[202:203]
	v_pk_add_f32 v[208:209], v[34:35], v[208:209]
	v_pk_add_f32 v[210:211], v[36:37], v[210:211]
	global_store_dwordx4 v[212:213], v[196:199], off
	global_store_dwordx4 v[212:213], v[200:203], off offset:512
	global_store_dwordx4 v[232:233], v[204:207], off
	global_store_dwordx4 v[232:233], v[208:211], off offset:512
	s_mov_b64 s[62:63], 0x10000
	v_lshl_add_u64 v[212:213], v[212:213], 0, s[62:63]
	v_lshl_add_u64 v[232:233], v[232:233], 0, s[62:63]
	v_mov_b32_dpp v228, v26 row_ror:8 row_mask:0xf bank_mask:0xf
	v_mov_b32_dpp v229, v27 row_ror:8 row_mask:0xf bank_mask:0xf
	v_mov_b32_dpp v230, v28 row_ror:8 row_mask:0xf bank_mask:0xf
	v_mov_b32_dpp v231, v29 row_ror:8 row_mask:0xf bank_mask:0xf
	v_mov_b32_dpp v234, v30 row_ror:8 row_mask:0xf bank_mask:0xf
	v_mov_b32_dpp v235, v31 row_ror:8 row_mask:0xf bank_mask:0xf
	v_mov_b32_dpp v236, v32 row_ror:8 row_mask:0xf bank_mask:0xf
	v_mov_b32_dpp v237, v33 row_ror:8 row_mask:0xf bank_mask:0xf
	v_cndmask_b32_e64 v30, v30, v228, s[60:61]
	v_cndmask_b32_e64 v31, v31, v229, s[60:61]
	v_cndmask_b32_e64 v32, v32, v230, s[60:61]
	v_cndmask_b32_e64 v33, v33, v231, s[60:61]
	v_cndmask_b32_e64 v26, v234, v26, s[60:61]
	v_cndmask_b32_e64 v27, v235, v27, s[60:61]
	v_cndmask_b32_e64 v28, v236, v28, s[60:61]
	v_cndmask_b32_e64 v29, v237, v29, s[60:61]
	v_mov_b32_dpp v228, v18 row_ror:8 row_mask:0xf bank_mask:0xf
	v_mov_b32_dpp v229, v19 row_ror:8 row_mask:0xf bank_mask:0xf
	v_mov_b32_dpp v230, v20 row_ror:8 row_mask:0xf bank_mask:0xf
	v_mov_b32_dpp v231, v21 row_ror:8 row_mask:0xf bank_mask:0xf
	v_mov_b32_dpp v234, v22 row_ror:8 row_mask:0xf bank_mask:0xf
	v_mov_b32_dpp v235, v23 row_ror:8 row_mask:0xf bank_mask:0xf
	v_mov_b32_dpp v236, v24 row_ror:8 row_mask:0xf bank_mask:0xf
	v_mov_b32_dpp v237, v25 row_ror:8 row_mask:0xf bank_mask:0xf
	v_cndmask_b32_e64 v22, v22, v228, s[60:61]
	v_cndmask_b32_e64 v23, v23, v229, s[60:61]
	v_cndmask_b32_e64 v24, v24, v230, s[60:61]
	v_cndmask_b32_e64 v25, v25, v231, s[60:61]
	v_cndmask_b32_e64 v18, v234, v18, s[60:61]
	v_cndmask_b32_e64 v19, v235, v19, s[60:61]
	v_cndmask_b32_e64 v20, v236, v20, s[60:61]
	v_cndmask_b32_e64 v21, v237, v21, s[60:61]
	s_waitcnt vmcnt(12)
; #define PG8_WAIT_V(n) asm volatile("s_waitcnt vmcnt(" #n ")" ::: "memory")
; #define PG8_BAR __builtin_amdgcn_s_barrier()
; template <class Epi, class Sched>
; __device__ __forceinline__ void gemm_phase(PG8_LAS unsigned char* lds, const Gemm g, const Sched& S, const Epi& E) {
;     ...
;         E(acc, cur, wr, wc, fr, fq);
;         if (!has_next) break;
; #pragma unroll
;         for (int a = 0; a < 2; ++a)
; #pragma unroll
;             for (int b = 0; b < 2; ++b)
; #pragma unroll
;                 for (int m = 0; m < 4; ++m)
; #pragma unroll
;                     for (int n = 0; n < 2; ++n) acc[a][b][m][n] = (f32x4){0.f, 0.f, 0.f, 0.f};
;         cur = nxt; cA = nA; cB = nB; ++ui;
;     }
;     PG8_WAIT_V(0);
;     if (wr == 0) PG8_BAR;
;     PG8_BAR;
;   __device__ __forceinline__ void operator()(const acc8_t& acc, const pg8::Unit& u, int wr, int wc, int fr, int fq) const {
;     ...
;     for (int ai = 0; ai < 2; ai++)
; #pragma unroll
;       for (int m = 0; m < 4; m++) {
;         const size_t token = EPI_TOKEN(u, ai, m);
; #pragma unroll
;         for (int bj = 0; bj < 2; bj++)
; #pragma unroll
;           for (int n = 0; n < 2; n++) {
;             float* yp = out + O_Y + token * 1024 + EPI_COL(u, bj, n);
;             float4 y = *(const float4*)yp;
;             y.x += acc[ai][bj][m][n][0]; y.y += acc[ai][bj][m][n][1]; y.z += acc[ai][bj][m][n][2]; y.w += acc[ai][bj][m][n][3];
;             *(float4*)yp = y;
;           }
	v_pk_add_f32 v[164:165], v[30:31], v[164:165]
	v_pk_add_f32 v[166:167], v[32:33], v[166:167]
	v_pk_add_f32 v[172:173], v[26:27], v[172:173]
	v_pk_add_f32 v[174:175], v[28:29], v[174:175]
	v_pk_add_f32 v[168:169], v[22:23], v[168:169]
	v_pk_add_f32 v[170:171], v[24:25], v[170:171]
	v_pk_add_f32 v[176:177], v[18:19], v[176:177]
	v_pk_add_f32 v[178:179], v[20:21], v[178:179]
	global_store_dwordx4 v[212:213], v[164:167], off
	global_store_dwordx4 v[212:213], v[168:171], off offset:512
	global_store_dwordx4 v[232:233], v[172:175], off
	global_store_dwordx4 v[232:233], v[176:179], off offset:512
	s_mov_b64 s[62:63], 0x10000
	v_lshl_add_u64 v[212:213], v[212:213], 0, s[62:63]
	v_lshl_add_u64 v[232:233], v[232:233], 0, s[62:63]
	v_mov_b32_dpp v228, v10 row_ror:8 row_mask:0xf bank_mask:0xf
	v_mov_b32_dpp v229, v11 row_ror:8 row_mask:0xf bank_mask:0xf
	v_mov_b32_dpp v230, v12 row_ror:8 row_mask:0xf bank_mask:0xf
	v_mov_b32_dpp v231, v13 row_ror:8 row_mask:0xf bank_mask:0xf
	v_mov_b32_dpp v234, v14 row_ror:8 row_mask:0xf bank_mask:0xf
	v_mov_b32_dpp v235, v15 row_ror:8 row_mask:0xf bank_mask:0xf
	v_mov_b32_dpp v236, v16 row_ror:8 row_mask:0xf bank_mask:0xf
	v_mov_b32_dpp v237, v17 row_ror:8 row_mask:0xf bank_mask:0xf
	v_cndmask_b32_e64 v14, v14, v228, s[60:61]
	v_cndmask_b32_e64 v15, v15, v229, s[60:61]
	v_cndmask_b32_e64 v16, v16, v230, s[60:61]
	v_cndmask_b32_e64 v17, v17, v231, s[60:61]
	v_cndmask_b32_e64 v10, v234, v10, s[60:61]
	v_cndmask_b32_e64 v11, v235, v11, s[60:61]
	v_cndmask_b32_e64 v12, v236, v12, s[60:61]
	v_cndmask_b32_e64 v13, v237, v13, s[60:61]
	v_mov_b32_dpp v228, v2 row_ror:8 row_mask:0xf bank_mask:0xf
	v_mov_b32_dpp v229, v3 row_ror:8 row_mask:0xf bank_mask:0xf
	v_mov_b32_dpp v230, v4 row_ror:8 row_mask:0xf bank_mask:0xf
	v_mov_b32_dpp v231, v5 row_ror:8 row_mask:0xf bank_mask:0xf
	v_mov_b32_dpp v234, v6 row_ror:8 row_mask:0xf bank_mask:0xf
	v_mov_b32_dpp v235, v7 row_ror:8 row_mask:0xf bank_mask:0xf
	v_mov_b32_dpp v236, v8 row_ror:8 row_mask:0xf bank_mask:0xf
	v_mov_b32_dpp v237, v9 row_ror:8 row_mask:0xf bank_mask:0xf
	v_cndmask_b32_e64 v6, v6, v228, s[60:61]
	v_cndmask_b32_e64 v7, v7, v229, s[60:61]
	v_cndmask_b32_e64 v8, v8, v230, s[60:61]
	v_cndmask_b32_e64 v9, v9, v231, s[60:61]
	v_cndmask_b32_e64 v2, v234, v2, s[60:61]
	v_cndmask_b32_e64 v3, v235, v3, s[60:61]
	v_cndmask_b32_e64 v4, v236, v4, s[60:61]
	v_cndmask_b32_e64 v5, v237, v5, s[60:61]
	s_waitcnt vmcnt(8)
	v_pk_add_f32 v[180:181], v[14:15], v[180:181]
	v_pk_add_f32 v[182:183], v[16:17], v[182:183]
	v_pk_add_f32 v[188:189], v[10:11], v[188:189]
	v_pk_add_f32 v[190:191], v[12:13], v[190:191]
	v_pk_add_f32 v[184:185], v[6:7], v[184:185]
	v_pk_add_f32 v[186:187], v[8:9], v[186:187]
	v_pk_add_f32 v[192:193], v[2:3], v[192:193]
	v_pk_add_f32 v[194:195], v[4:5], v[194:195]
	global_store_dwordx4 v[212:213], v[180:183], off
	global_store_dwordx4 v[212:213], v[184:187], off offset:512
	global_store_dwordx4 v[232:233], v[188:191], off
	global_store_dwordx4 v[232:233], v[192:195], off offset:512
	s_and_b64 vcc, exec, s[12:13]
	s_cbranch_vccz .LBB0_825
	s_waitcnt vmcnt(0)
	s_cmpk_gt_u32 s34, 0xff
	s_cbranch_scc1 .LBB0_832
	s_barrier
